# K-loop edges: loop-back barrier rotated behind the counter and exit-test SALU; next-tile pointer select moved behind the segment's DMA issues (all six GEMM loops)
# speedup vs baseline: 1.0017x; 1.0017x over previous
.LBB0_175:
	ds_read_b128 v[148:151], v159
	ds_read_b128 v[152:155], v159 offset:1024
	ds_read_b128 v[164:167], v159 offset:2048
	ds_read_b128 v[168:171], v159 offset:3072
	ds_read_b128 v[172:175], v160
	ds_read_b128 v[176:179], v160 offset:1024
	ds_read_b128 v[180:183], v160 offset:2048
	ds_read_b128 v[184:187], v160 offset:3072
	v_lshl_add_u64 v[220:221], s[60:61], 0, v[140:141]
	s_add_i32 m0, s72, 0xc000
	ds_read_b128 v[188:191], v161
	ds_read_b128 v[192:195], v161 offset:1024
	ds_read_b128 v[196:199], v161 offset:2048
	ds_read_b128 v[200:203], v161 offset:3072
	ds_read_b128 v[204:207], v161 offset:4096
	ds_read_b128 v[208:211], v161 offset:5120
	ds_read_b128 v[212:215], v161 offset:6144
	ds_read_b128 v[216:219], v161 offset:7168
	global_load_lds_dwordx4 v[220:221], off
	v_lshl_add_u64 v[220:221], s[60:61], 0, v[142:143]
	s_add_i32 m0, s72, 0xe000
	s_nop 0
	global_load_lds_dwordx4 v[220:221], off
	s_add_u32 s6, s60, 0xfffc0080
	s_addc_u32 s7, s61, -1
	s_cmp_eq_u32 s63, 12
	s_cselect_b32 s67, s5, s7
	s_cselect_b32 s66, s8, s6
	s_cselect_b32 s65, s30, s55
	s_cselect_b32 s64, s31, s49
	s_waitcnt vmcnt(8)
	s_waitcnt lgkmcnt(0)
	s_barrier
	s_setprio 1
	s_waitcnt lgkmcnt(0)
	v_mfma_f32_16x16x32_bf16 v[126:129], v[148:151], v[188:191], v[126:129]
	v_mfma_f32_16x16x32_bf16 v[122:125], v[164:167], v[188:191], v[122:125]
	v_mfma_f32_16x16x32_bf16 v[110:113], v[148:151], v[196:199], v[110:113]
	v_mfma_f32_16x16x32_bf16 v[106:109], v[164:167], v[196:199], v[106:109]
	v_mfma_f32_16x16x32_bf16 v[94:97], v[148:151], v[204:207], v[94:97]
	v_mfma_f32_16x16x32_bf16 v[90:93], v[164:167], v[204:207], v[90:93]
	v_mfma_f32_16x16x32_bf16 v[78:81], v[148:151], v[212:215], v[78:81]
	v_mfma_f32_16x16x32_bf16 v[74:77], v[164:167], v[212:215], v[74:77]
	v_mfma_f32_16x16x32_bf16 v[126:129], v[152:155], v[192:195], v[126:129]
	v_mfma_f32_16x16x32_bf16 v[122:125], v[168:171], v[192:195], v[122:125]
	v_mfma_f32_16x16x32_bf16 v[110:113], v[152:155], v[200:203], v[110:113]
	v_mfma_f32_16x16x32_bf16 v[106:109], v[168:171], v[200:203], v[106:109]
	v_mfma_f32_16x16x32_bf16 v[94:97], v[152:155], v[208:211], v[94:97]
	v_mfma_f32_16x16x32_bf16 v[90:93], v[168:171], v[208:211], v[90:93]
	v_mfma_f32_16x16x32_bf16 v[78:81], v[152:155], v[216:219], v[78:81]
	v_mfma_f32_16x16x32_bf16 v[74:77], v[168:171], v[216:219], v[74:77]
	s_setprio 0
	s_setprio 1
	v_mfma_f32_16x16x32_bf16 v[118:121], v[172:175], v[188:191], v[118:121]
	v_mfma_f32_16x16x32_bf16 v[114:117], v[180:183], v[188:191], v[114:117]
	v_mfma_f32_16x16x32_bf16 v[102:105], v[172:175], v[196:199], v[102:105]
	v_mfma_f32_16x16x32_bf16 v[98:101], v[180:183], v[196:199], v[98:101]
	v_mfma_f32_16x16x32_bf16 v[86:89], v[172:175], v[204:207], v[86:89]
	v_mfma_f32_16x16x32_bf16 v[82:85], v[180:183], v[204:207], v[82:85]
	v_mfma_f32_16x16x32_bf16 v[70:73], v[172:175], v[212:215], v[70:73]
	v_mfma_f32_16x16x32_bf16 v[66:69], v[180:183], v[212:215], v[66:69]
	v_mfma_f32_16x16x32_bf16 v[118:121], v[176:179], v[192:195], v[118:121]
	v_mfma_f32_16x16x32_bf16 v[114:117], v[184:187], v[192:195], v[114:117]
	v_mfma_f32_16x16x32_bf16 v[102:105], v[176:179], v[200:203], v[102:105]
	v_mfma_f32_16x16x32_bf16 v[98:101], v[184:187], v[200:203], v[98:101]
	v_mfma_f32_16x16x32_bf16 v[86:89], v[176:179], v[208:211], v[86:89]
	v_mfma_f32_16x16x32_bf16 v[82:85], v[184:187], v[208:211], v[82:85]
	v_mfma_f32_16x16x32_bf16 v[70:73], v[176:179], v[216:219], v[70:73]
	v_mfma_f32_16x16x32_bf16 v[66:69], v[184:187], v[216:219], v[66:69]
	s_setprio 0
	s_barrier
	s_add_i32 s6, s85, s47
	v_lshl_add_u64 v[220:221], s[64:65], 0, v[132:133]
	s_mov_b32 m0, s6
	ds_read_b128 v[188:191], v161 offset:16384
	ds_read_b128 v[192:195], v161 offset:17408
	ds_read_b128 v[196:199], v161 offset:18432
	ds_read_b128 v[200:203], v161 offset:19456
	ds_read_b128 v[204:207], v161 offset:20480
	ds_read_b128 v[208:211], v161 offset:21504
	ds_read_b128 v[212:215], v161 offset:22528
	ds_read_b128 v[216:219], v161 offset:23552
	global_load_lds_dwordx4 v[220:221], off
	s_add_i32 m0, s6, 0x2000
	s_add_u32 s6, s64, 0x40000
	v_lshl_add_u64 v[222:223], s[64:65], 0, v[136:137]
	s_addc_u32 s7, s65, 0
	s_add_i32 s88, s86, s47
	global_load_lds_dwordx4 v[222:223], off
	v_lshl_add_u64 v[224:225], s[6:7], 0, v[132:133]
	s_mov_b32 m0, s88
	v_lshl_add_u64 v[226:227], s[66:67], 0, v[134:135]
	global_load_lds_dwordx4 v[224:225], off
	v_lshl_add_u64 v[224:225], s[6:7], 0, v[136:137]
	s_add_i32 m0, s88, 0x2000
	s_nop 0
	global_load_lds_dwordx4 v[224:225], off
	v_lshl_add_u64 v[224:225], s[66:67], 0, v[130:131]
	s_mov_b32 m0, s72
	s_nop 0
	global_load_lds_dwordx4 v[224:225], off
	s_mov_b32 m0, s73
	s_nop 0
	global_load_lds_dwordx4 v[226:227], off
	s_waitcnt vmcnt(8)
	s_waitcnt lgkmcnt(0)
	s_barrier
	s_setprio 1
	s_waitcnt lgkmcnt(0)
	v_mfma_f32_16x16x32_bf16 v[62:65], v[148:151], v[188:191], v[62:65]
	v_mfma_f32_16x16x32_bf16 v[58:61], v[164:167], v[188:191], v[58:61]
	v_mfma_f32_16x16x32_bf16 v[46:49], v[148:151], v[196:199], v[46:49]
	v_mfma_f32_16x16x32_bf16 v[42:45], v[164:167], v[196:199], v[42:45]
	v_mfma_f32_16x16x32_bf16 v[30:33], v[148:151], v[204:207], v[30:33]
	v_mfma_f32_16x16x32_bf16 v[26:29], v[164:167], v[204:207], v[26:29]
	v_mfma_f32_16x16x32_bf16 v[14:17], v[148:151], v[212:215], v[14:17]
	v_mfma_f32_16x16x32_bf16 v[10:13], v[164:167], v[212:215], v[10:13]
	v_mfma_f32_16x16x32_bf16 v[62:65], v[152:155], v[192:195], v[62:65]
	v_mfma_f32_16x16x32_bf16 v[58:61], v[168:171], v[192:195], v[58:61]
	v_mfma_f32_16x16x32_bf16 v[46:49], v[152:155], v[200:203], v[46:49]
	v_mfma_f32_16x16x32_bf16 v[42:45], v[168:171], v[200:203], v[42:45]
	v_mfma_f32_16x16x32_bf16 v[30:33], v[152:155], v[208:211], v[30:33]
	v_mfma_f32_16x16x32_bf16 v[26:29], v[168:171], v[208:211], v[26:29]
	v_mfma_f32_16x16x32_bf16 v[14:17], v[152:155], v[216:219], v[14:17]
	v_mfma_f32_16x16x32_bf16 v[10:13], v[168:171], v[216:219], v[10:13]
	s_setprio 0
	s_setprio 1
	v_mfma_f32_16x16x32_bf16 v[54:57], v[172:175], v[188:191], v[54:57]
	v_mfma_f32_16x16x32_bf16 v[50:53], v[180:183], v[188:191], v[50:53]
	v_mfma_f32_16x16x32_bf16 v[38:41], v[172:175], v[196:199], v[38:41]
	v_mfma_f32_16x16x32_bf16 v[34:37], v[180:183], v[196:199], v[34:37]
	v_mfma_f32_16x16x32_bf16 v[22:25], v[172:175], v[204:207], v[22:25]
	v_mfma_f32_16x16x32_bf16 v[18:21], v[180:183], v[204:207], v[18:21]
	v_mfma_f32_16x16x32_bf16 v[6:9], v[172:175], v[212:215], v[6:9]
	v_mfma_f32_16x16x32_bf16 v[2:5], v[180:183], v[212:215], v[2:5]
	v_mfma_f32_16x16x32_bf16 v[54:57], v[176:179], v[192:195], v[54:57]
	v_mfma_f32_16x16x32_bf16 v[50:53], v[184:187], v[192:195], v[50:53]
	v_mfma_f32_16x16x32_bf16 v[38:41], v[176:179], v[200:203], v[38:41]
	v_mfma_f32_16x16x32_bf16 v[34:37], v[184:187], v[200:203], v[34:37]
	v_mfma_f32_16x16x32_bf16 v[22:25], v[176:179], v[208:211], v[22:25]
	v_mfma_f32_16x16x32_bf16 v[18:21], v[184:187], v[208:211], v[18:21]
	v_mfma_f32_16x16x32_bf16 v[6:9], v[176:179], v[216:219], v[6:9]
	v_mfma_f32_16x16x32_bf16 v[2:5], v[184:187], v[216:219], v[2:5]
	s_setprio 0
	s_barrier
	s_add_i32 s88, 0, 0x18000
	v_add_u32_e32 v138, s88, v158
	s_add_i32 s89, 0, 0x1c000
	ds_read_b128 v[148:151], v138
	ds_read_b128 v[152:155], v138 offset:1024
	ds_read_b128 v[164:167], v138 offset:2048
	ds_read_b128 v[168:171], v138 offset:3072
	v_add_u32_e32 v138, s89, v158
	ds_read_b128 v[172:175], v138
	ds_read_b128 v[176:179], v138 offset:1024
	ds_read_b128 v[180:183], v138 offset:2048
	ds_read_b128 v[184:187], v138 offset:3072
	s_add_u32 s6, s66, 0x40000
	s_addc_u32 s7, s67, 0
	s_mov_b32 m0, s74
	v_lshl_add_u64 v[228:229], s[6:7], 0, v[130:131]
	ds_read_b128 v[188:191], v161 offset:32768
	ds_read_b128 v[192:195], v161 offset:33792
	ds_read_b128 v[196:199], v161 offset:34816
	ds_read_b128 v[200:203], v161 offset:35840
	ds_read_b128 v[204:207], v161 offset:36864
	ds_read_b128 v[208:211], v161 offset:37888
	ds_read_b128 v[212:215], v161 offset:38912
	ds_read_b128 v[216:219], v161 offset:39936
	global_load_lds_dwordx4 v[228:229], off
	v_lshl_add_u64 v[228:229], s[6:7], 0, v[134:135]
	s_mov_b32 m0, s75
	s_nop 0
	global_load_lds_dwordx4 v[228:229], off
	s_waitcnt vmcnt(8)
	s_waitcnt lgkmcnt(0)
	s_barrier
	s_setprio 1
	s_waitcnt lgkmcnt(0)
	v_mfma_f32_16x16x32_bf16 v[126:129], v[148:151], v[188:191], v[126:129]
	v_mfma_f32_16x16x32_bf16 v[122:125], v[164:167], v[188:191], v[122:125]
	v_mfma_f32_16x16x32_bf16 v[110:113], v[148:151], v[196:199], v[110:113]
	v_mfma_f32_16x16x32_bf16 v[106:109], v[164:167], v[196:199], v[106:109]
	v_mfma_f32_16x16x32_bf16 v[94:97], v[148:151], v[204:207], v[94:97]
	v_mfma_f32_16x16x32_bf16 v[90:93], v[164:167], v[204:207], v[90:93]
	v_mfma_f32_16x16x32_bf16 v[78:81], v[148:151], v[212:215], v[78:81]
	v_mfma_f32_16x16x32_bf16 v[74:77], v[164:167], v[212:215], v[74:77]
	v_mfma_f32_16x16x32_bf16 v[126:129], v[152:155], v[192:195], v[126:129]
	v_mfma_f32_16x16x32_bf16 v[122:125], v[168:171], v[192:195], v[122:125]
	v_mfma_f32_16x16x32_bf16 v[110:113], v[152:155], v[200:203], v[110:113]
	v_mfma_f32_16x16x32_bf16 v[106:109], v[168:171], v[200:203], v[106:109]
	v_mfma_f32_16x16x32_bf16 v[94:97], v[152:155], v[208:211], v[94:97]
	v_mfma_f32_16x16x32_bf16 v[90:93], v[168:171], v[208:211], v[90:93]
	v_mfma_f32_16x16x32_bf16 v[78:81], v[152:155], v[216:219], v[78:81]
	v_mfma_f32_16x16x32_bf16 v[74:77], v[168:171], v[216:219], v[74:77]
	s_setprio 0
	s_setprio 1
	v_mfma_f32_16x16x32_bf16 v[118:121], v[172:175], v[188:191], v[118:121]
	v_mfma_f32_16x16x32_bf16 v[114:117], v[180:183], v[188:191], v[114:117]
	v_mfma_f32_16x16x32_bf16 v[102:105], v[172:175], v[196:199], v[102:105]
	v_mfma_f32_16x16x32_bf16 v[98:101], v[180:183], v[196:199], v[98:101]
	v_mfma_f32_16x16x32_bf16 v[86:89], v[172:175], v[204:207], v[86:89]
	v_mfma_f32_16x16x32_bf16 v[82:85], v[180:183], v[204:207], v[82:85]
	v_mfma_f32_16x16x32_bf16 v[70:73], v[172:175], v[212:215], v[70:73]
	v_mfma_f32_16x16x32_bf16 v[66:69], v[180:183], v[212:215], v[66:69]
	v_mfma_f32_16x16x32_bf16 v[118:121], v[176:179], v[192:195], v[118:121]
	v_mfma_f32_16x16x32_bf16 v[114:117], v[184:187], v[192:195], v[114:117]
	v_mfma_f32_16x16x32_bf16 v[102:105], v[176:179], v[200:203], v[102:105]
	v_mfma_f32_16x16x32_bf16 v[98:101], v[184:187], v[200:203], v[98:101]
	v_mfma_f32_16x16x32_bf16 v[86:89], v[176:179], v[208:211], v[86:89]
	v_mfma_f32_16x16x32_bf16 v[82:85], v[184:187], v[208:211], v[82:85]
	v_mfma_f32_16x16x32_bf16 v[70:73], v[176:179], v[216:219], v[70:73]
	v_mfma_f32_16x16x32_bf16 v[66:69], v[184:187], v[216:219], v[66:69]
	s_setprio 0
	s_barrier
	s_add_i32 s6, s88, s47
	v_lshl_add_u64 v[220:221], v[220:221], 0, s[20:21]
	s_mov_b32 m0, s6
	ds_read_b128 v[188:191], v161 offset:49152
	ds_read_b128 v[192:195], v161 offset:50176
	ds_read_b128 v[196:199], v161 offset:51200
	ds_read_b128 v[200:203], v161 offset:52224
	ds_read_b128 v[204:207], v161 offset:53248
	ds_read_b128 v[208:211], v161 offset:54272
	ds_read_b128 v[212:215], v161 offset:55296
	ds_read_b128 v[216:219], v161 offset:56320
	global_load_lds_dwordx4 v[220:221], off
	s_add_i32 m0, s6, 0x2000
	s_add_u32 s6, s64, 0x40080
	v_lshl_add_u64 v[220:221], v[222:223], 0, s[20:21]
	s_addc_u32 s7, s65, 0
	s_add_i32 s64, s89, s47
	global_load_lds_dwordx4 v[220:221], off
	v_lshl_add_u64 v[220:221], s[6:7], 0, v[132:133]
	s_mov_b32 m0, s64
	s_nop 0
	global_load_lds_dwordx4 v[220:221], off
	v_lshl_add_u64 v[220:221], s[6:7], 0, v[136:137]
	s_add_i32 m0, s64, 0x2000
	s_nop 0
	global_load_lds_dwordx4 v[220:221], off
	v_lshl_add_u64 v[220:221], v[224:225], 0, s[20:21]
	s_mov_b32 m0, s77
	s_nop 0
	global_load_lds_dwordx4 v[220:221], off
	v_lshl_add_u64 v[220:221], v[226:227], 0, s[20:21]
	s_mov_b32 m0, s78
	s_nop 0
	global_load_lds_dwordx4 v[220:221], off
	s_waitcnt vmcnt(8)
	s_waitcnt lgkmcnt(0)
	s_barrier
	s_setprio 1
	s_waitcnt lgkmcnt(0)
	v_mfma_f32_16x16x32_bf16 v[62:65], v[148:151], v[188:191], v[62:65]
	v_mfma_f32_16x16x32_bf16 v[58:61], v[164:167], v[188:191], v[58:61]
	v_mfma_f32_16x16x32_bf16 v[46:49], v[148:151], v[196:199], v[46:49]
	v_mfma_f32_16x16x32_bf16 v[42:45], v[164:167], v[196:199], v[42:45]
	v_mfma_f32_16x16x32_bf16 v[30:33], v[148:151], v[204:207], v[30:33]
	v_mfma_f32_16x16x32_bf16 v[26:29], v[164:167], v[204:207], v[26:29]
	v_mfma_f32_16x16x32_bf16 v[14:17], v[148:151], v[212:215], v[14:17]
	v_mfma_f32_16x16x32_bf16 v[10:13], v[164:167], v[212:215], v[10:13]
	v_mfma_f32_16x16x32_bf16 v[62:65], v[152:155], v[192:195], v[62:65]
	v_mfma_f32_16x16x32_bf16 v[58:61], v[168:171], v[192:195], v[58:61]
	v_mfma_f32_16x16x32_bf16 v[46:49], v[152:155], v[200:203], v[46:49]
	v_mfma_f32_16x16x32_bf16 v[42:45], v[168:171], v[200:203], v[42:45]
	v_mfma_f32_16x16x32_bf16 v[30:33], v[152:155], v[208:211], v[30:33]
	v_mfma_f32_16x16x32_bf16 v[26:29], v[168:171], v[208:211], v[26:29]
	v_mfma_f32_16x16x32_bf16 v[14:17], v[152:155], v[216:219], v[14:17]
	v_mfma_f32_16x16x32_bf16 v[10:13], v[168:171], v[216:219], v[10:13]
	s_setprio 0
	s_setprio 1
	v_mfma_f32_16x16x32_bf16 v[54:57], v[172:175], v[188:191], v[54:57]
	v_mfma_f32_16x16x32_bf16 v[50:53], v[180:183], v[188:191], v[50:53]
	v_mfma_f32_16x16x32_bf16 v[38:41], v[172:175], v[196:199], v[38:41]
	v_mfma_f32_16x16x32_bf16 v[34:37], v[180:183], v[196:199], v[34:37]
	v_mfma_f32_16x16x32_bf16 v[22:25], v[172:175], v[204:207], v[22:25]
	v_mfma_f32_16x16x32_bf16 v[18:21], v[180:183], v[204:207], v[18:21]
	v_mfma_f32_16x16x32_bf16 v[6:9], v[172:175], v[212:215], v[6:9]
	v_mfma_f32_16x16x32_bf16 v[2:5], v[180:183], v[212:215], v[2:5]
	v_mfma_f32_16x16x32_bf16 v[54:57], v[176:179], v[192:195], v[54:57]
	v_mfma_f32_16x16x32_bf16 v[50:53], v[184:187], v[192:195], v[50:53]
	v_mfma_f32_16x16x32_bf16 v[38:41], v[176:179], v[200:203], v[38:41]
	v_mfma_f32_16x16x32_bf16 v[34:37], v[184:187], v[200:203], v[34:37]
	v_mfma_f32_16x16x32_bf16 v[22:25], v[176:179], v[208:211], v[22:25]
	v_mfma_f32_16x16x32_bf16 v[18:21], v[184:187], v[208:211], v[18:21]
	v_mfma_f32_16x16x32_bf16 v[6:9], v[176:179], v[216:219], v[6:9]
	v_mfma_f32_16x16x32_bf16 v[2:5], v[184:187], v[216:219], v[2:5]
	s_setprio 0
	s_add_i32 s63, s63, 2
	s_add_u32 s60, s60, 0x100
	s_addc_u32 s61, s61, 0
	s_add_u32 s49, s49, 0x100
	s_addc_u32 s55, s55, 0
	s_cmp_gt_u32 s63, 13
	s_barrier
	s_cbranch_scc0 .LBB0_175

.LBB0_560:
	ds_read_b128 v[154:157], v150
	ds_read_b128 v[158:161], v150 offset:1024
	ds_read_b128 v[162:165], v150 offset:2048
	ds_read_b128 v[166:169], v150 offset:3072
	ds_read_b128 v[170:173], v151
	ds_read_b128 v[174:177], v151 offset:1024
	ds_read_b128 v[178:181], v151 offset:2048
	ds_read_b128 v[182:185], v151 offset:3072
	v_lshl_add_u64 v[146:147], s[66:67], 0, v[138:139]
	s_add_i32 m0, s65, 0xc000
	ds_read_b128 v[186:189], v152
	ds_read_b128 v[190:193], v152 offset:1024
	ds_read_b128 v[194:197], v152 offset:2048
	ds_read_b128 v[198:201], v152 offset:3072
	ds_read_b128 v[202:205], v152 offset:4096
	ds_read_b128 v[206:209], v152 offset:5120
	ds_read_b128 v[210:213], v152 offset:6144
	ds_read_b128 v[214:217], v152 offset:7168
	global_load_lds_dwordx4 v[146:147], off
	v_lshl_add_u64 v[146:147], s[66:67], 0, v[140:141]
	s_add_i32 m0, s65, 0xe000
	s_nop 0
	global_load_lds_dwordx4 v[146:147], off
	s_add_u32 s6, s66, 0xfffe0080
	s_addc_u32 s7, s67, -1
	s_cmp_eq_u32 s96, 4
	s_cselect_b32 s73, s59, s7
	s_cselect_b32 s72, s92, s6
	s_cselect_b32 s71, s57, s95
	s_cselect_b32 s70, s93, s94
	s_waitcnt vmcnt(8)
	s_waitcnt lgkmcnt(0)
	s_barrier
	s_setprio 1
	s_waitcnt lgkmcnt(0)
	v_mfma_f32_16x16x32_bf16 v[126:129], v[154:157], v[186:189], v[126:129]
	v_mfma_f32_16x16x32_bf16 v[122:125], v[162:165], v[186:189], v[122:125]
	v_mfma_f32_16x16x32_bf16 v[114:117], v[154:157], v[194:197], v[114:117]
	v_mfma_f32_16x16x32_bf16 v[106:109], v[162:165], v[194:197], v[106:109]
	v_mfma_f32_16x16x32_bf16 v[98:101], v[154:157], v[202:205], v[98:101]
	v_mfma_f32_16x16x32_bf16 v[90:93], v[162:165], v[202:205], v[90:93]
	v_mfma_f32_16x16x32_bf16 v[82:85], v[154:157], v[210:213], v[82:85]
	v_mfma_f32_16x16x32_bf16 v[74:77], v[162:165], v[210:213], v[74:77]
	v_mfma_f32_16x16x32_bf16 v[126:129], v[158:161], v[190:193], v[126:129]
	v_mfma_f32_16x16x32_bf16 v[122:125], v[166:169], v[190:193], v[122:125]
	v_mfma_f32_16x16x32_bf16 v[114:117], v[158:161], v[198:201], v[114:117]
	v_mfma_f32_16x16x32_bf16 v[106:109], v[166:169], v[198:201], v[106:109]
	v_mfma_f32_16x16x32_bf16 v[98:101], v[158:161], v[206:209], v[98:101]
	v_mfma_f32_16x16x32_bf16 v[90:93], v[166:169], v[206:209], v[90:93]
	v_mfma_f32_16x16x32_bf16 v[82:85], v[158:161], v[214:217], v[82:85]
	v_mfma_f32_16x16x32_bf16 v[74:77], v[166:169], v[214:217], v[74:77]
	s_setprio 0
	s_setprio 1
	v_mfma_f32_16x16x32_bf16 v[118:121], v[170:173], v[186:189], v[118:121]
	v_mfma_f32_16x16x32_bf16 v[110:113], v[178:181], v[186:189], v[110:113]
	v_mfma_f32_16x16x32_bf16 v[102:105], v[170:173], v[194:197], v[102:105]
	v_mfma_f32_16x16x32_bf16 v[94:97], v[178:181], v[194:197], v[94:97]
	v_mfma_f32_16x16x32_bf16 v[86:89], v[170:173], v[202:205], v[86:89]
	v_mfma_f32_16x16x32_bf16 v[78:81], v[178:181], v[202:205], v[78:81]
	v_mfma_f32_16x16x32_bf16 v[70:73], v[170:173], v[210:213], v[70:73]
	v_mfma_f32_16x16x32_bf16 v[66:69], v[178:181], v[210:213], v[66:69]
	v_mfma_f32_16x16x32_bf16 v[118:121], v[174:177], v[190:193], v[118:121]
	v_mfma_f32_16x16x32_bf16 v[110:113], v[182:185], v[190:193], v[110:113]
	v_mfma_f32_16x16x32_bf16 v[102:105], v[174:177], v[198:201], v[102:105]
	v_mfma_f32_16x16x32_bf16 v[94:97], v[182:185], v[198:201], v[94:97]
	v_mfma_f32_16x16x32_bf16 v[86:89], v[174:177], v[206:209], v[86:89]
	v_mfma_f32_16x16x32_bf16 v[78:81], v[182:185], v[206:209], v[78:81]
	v_mfma_f32_16x16x32_bf16 v[70:73], v[174:177], v[214:217], v[70:73]
	v_mfma_f32_16x16x32_bf16 v[66:69], v[182:185], v[214:217], v[66:69]
	s_setprio 0
	s_barrier
	s_add_i32 s6, s85, s31
	v_lshl_add_u64 v[146:147], s[70:71], 0, v[132:133]
	s_mov_b32 m0, s6
	ds_read_b128 v[186:189], v152 offset:16384
	ds_read_b128 v[190:193], v152 offset:17408
	ds_read_b128 v[194:197], v152 offset:18432
	ds_read_b128 v[198:201], v152 offset:19456
	ds_read_b128 v[202:205], v152 offset:20480
	ds_read_b128 v[206:209], v152 offset:21504
	ds_read_b128 v[210:213], v152 offset:22528
	ds_read_b128 v[214:217], v152 offset:23552
	global_load_lds_dwordx4 v[146:147], off
	s_add_i32 m0, s6, 0x2000
	s_add_u32 s6, s70, 0x20000
	v_lshl_add_u64 v[218:219], s[70:71], 0, v[136:137]
	s_addc_u32 s7, s71, 0
	s_add_i32 s97, s86, s31
	global_load_lds_dwordx4 v[218:219], off
	v_lshl_add_u64 v[220:221], s[6:7], 0, v[132:133]
	s_mov_b32 m0, s97
	v_lshl_add_u64 v[222:223], s[72:73], 0, v[134:135]
	global_load_lds_dwordx4 v[220:221], off
	v_lshl_add_u64 v[220:221], s[6:7], 0, v[136:137]
	s_add_i32 m0, s97, 0x2000
	s_nop 0
	global_load_lds_dwordx4 v[220:221], off
	v_lshl_add_u64 v[220:221], s[72:73], 0, v[130:131]
	s_mov_b32 m0, s65
	s_nop 0
	global_load_lds_dwordx4 v[220:221], off
	s_mov_b32 m0, s76
	s_nop 0
	global_load_lds_dwordx4 v[222:223], off
	s_waitcnt vmcnt(8)
	s_waitcnt lgkmcnt(0)
	s_barrier
	s_setprio 1
	s_waitcnt lgkmcnt(0)
	v_mfma_f32_16x16x32_bf16 v[62:65], v[154:157], v[186:189], v[62:65]
	v_mfma_f32_16x16x32_bf16 v[58:61], v[162:165], v[186:189], v[58:61]
	v_mfma_f32_16x16x32_bf16 v[50:53], v[154:157], v[194:197], v[50:53]
	v_mfma_f32_16x16x32_bf16 v[42:45], v[162:165], v[194:197], v[42:45]
	v_mfma_f32_16x16x32_bf16 v[34:37], v[154:157], v[202:205], v[34:37]
	v_mfma_f32_16x16x32_bf16 v[26:29], v[162:165], v[202:205], v[26:29]
	v_mfma_f32_16x16x32_bf16 v[18:21], v[154:157], v[210:213], v[18:21]
	v_mfma_f32_16x16x32_bf16 v[10:13], v[162:165], v[210:213], v[10:13]
	v_mfma_f32_16x16x32_bf16 v[62:65], v[158:161], v[190:193], v[62:65]
	v_mfma_f32_16x16x32_bf16 v[58:61], v[166:169], v[190:193], v[58:61]
	v_mfma_f32_16x16x32_bf16 v[50:53], v[158:161], v[198:201], v[50:53]
	v_mfma_f32_16x16x32_bf16 v[42:45], v[166:169], v[198:201], v[42:45]
	v_mfma_f32_16x16x32_bf16 v[34:37], v[158:161], v[206:209], v[34:37]
	v_mfma_f32_16x16x32_bf16 v[26:29], v[166:169], v[206:209], v[26:29]
	v_mfma_f32_16x16x32_bf16 v[18:21], v[158:161], v[214:217], v[18:21]
	v_mfma_f32_16x16x32_bf16 v[10:13], v[166:169], v[214:217], v[10:13]
	s_setprio 0
	s_setprio 1
	v_mfma_f32_16x16x32_bf16 v[54:57], v[170:173], v[186:189], v[54:57]
	v_mfma_f32_16x16x32_bf16 v[46:49], v[178:181], v[186:189], v[46:49]
	v_mfma_f32_16x16x32_bf16 v[38:41], v[170:173], v[194:197], v[38:41]
	v_mfma_f32_16x16x32_bf16 v[30:33], v[178:181], v[194:197], v[30:33]
	v_mfma_f32_16x16x32_bf16 v[22:25], v[170:173], v[202:205], v[22:25]
	v_mfma_f32_16x16x32_bf16 v[14:17], v[178:181], v[202:205], v[14:17]
	v_mfma_f32_16x16x32_bf16 v[6:9], v[170:173], v[210:213], v[6:9]
	v_mfma_f32_16x16x32_bf16 v[2:5], v[178:181], v[210:213], v[2:5]
	v_mfma_f32_16x16x32_bf16 v[54:57], v[174:177], v[190:193], v[54:57]
	v_mfma_f32_16x16x32_bf16 v[46:49], v[182:185], v[190:193], v[46:49]
	v_mfma_f32_16x16x32_bf16 v[38:41], v[174:177], v[198:201], v[38:41]
	v_mfma_f32_16x16x32_bf16 v[30:33], v[182:185], v[198:201], v[30:33]
	v_mfma_f32_16x16x32_bf16 v[22:25], v[174:177], v[206:209], v[22:25]
	v_mfma_f32_16x16x32_bf16 v[14:17], v[182:185], v[206:209], v[14:17]
	v_mfma_f32_16x16x32_bf16 v[6:9], v[174:177], v[214:217], v[6:9]
	v_mfma_f32_16x16x32_bf16 v[2:5], v[182:185], v[214:217], v[2:5]
	s_setprio 0
	s_barrier
	s_add_i32 s97, 0, 0x18000
	v_add_u32_e32 v153, s97, v149
	s_add_i32 vcc_lo, 0, 0x1c000
	ds_read_b128 v[154:157], v153
	ds_read_b128 v[158:161], v153 offset:1024
	ds_read_b128 v[162:165], v153 offset:2048
	ds_read_b128 v[166:169], v153 offset:3072
	v_add_u32_e32 v153, vcc_lo, v149
	ds_read_b128 v[170:173], v153
	ds_read_b128 v[174:177], v153 offset:1024
	ds_read_b128 v[178:181], v153 offset:2048
	ds_read_b128 v[182:185], v153 offset:3072
	s_add_u32 s6, s72, 0x20000
	s_addc_u32 s7, s73, 0
	s_mov_b32 m0, s77
	v_lshl_add_u64 v[224:225], s[6:7], 0, v[130:131]
	ds_read_b128 v[186:189], v152 offset:32768
	ds_read_b128 v[190:193], v152 offset:33792
	ds_read_b128 v[194:197], v152 offset:34816
	ds_read_b128 v[198:201], v152 offset:35840
	ds_read_b128 v[202:205], v152 offset:36864
	ds_read_b128 v[206:209], v152 offset:37888
	ds_read_b128 v[210:213], v152 offset:38912
	ds_read_b128 v[214:217], v152 offset:39936
	global_load_lds_dwordx4 v[224:225], off
	v_lshl_add_u64 v[224:225], s[6:7], 0, v[134:135]
	s_mov_b32 m0, s78
	s_nop 0
	global_load_lds_dwordx4 v[224:225], off
	s_waitcnt vmcnt(8)
	s_waitcnt lgkmcnt(0)
	s_barrier
	s_setprio 1
	s_waitcnt lgkmcnt(0)
	v_mfma_f32_16x16x32_bf16 v[126:129], v[154:157], v[186:189], v[126:129]
	v_mfma_f32_16x16x32_bf16 v[122:125], v[162:165], v[186:189], v[122:125]
	v_mfma_f32_16x16x32_bf16 v[114:117], v[154:157], v[194:197], v[114:117]
	v_mfma_f32_16x16x32_bf16 v[106:109], v[162:165], v[194:197], v[106:109]
	v_mfma_f32_16x16x32_bf16 v[98:101], v[154:157], v[202:205], v[98:101]
	v_mfma_f32_16x16x32_bf16 v[90:93], v[162:165], v[202:205], v[90:93]
	v_mfma_f32_16x16x32_bf16 v[82:85], v[154:157], v[210:213], v[82:85]
	v_mfma_f32_16x16x32_bf16 v[74:77], v[162:165], v[210:213], v[74:77]
	v_mfma_f32_16x16x32_bf16 v[126:129], v[158:161], v[190:193], v[126:129]
	v_mfma_f32_16x16x32_bf16 v[122:125], v[166:169], v[190:193], v[122:125]
	v_mfma_f32_16x16x32_bf16 v[114:117], v[158:161], v[198:201], v[114:117]
	v_mfma_f32_16x16x32_bf16 v[106:109], v[166:169], v[198:201], v[106:109]
	v_mfma_f32_16x16x32_bf16 v[98:101], v[158:161], v[206:209], v[98:101]
	v_mfma_f32_16x16x32_bf16 v[90:93], v[166:169], v[206:209], v[90:93]
	v_mfma_f32_16x16x32_bf16 v[82:85], v[158:161], v[214:217], v[82:85]
	v_mfma_f32_16x16x32_bf16 v[74:77], v[166:169], v[214:217], v[74:77]
	s_setprio 0
	s_setprio 1
	v_mfma_f32_16x16x32_bf16 v[118:121], v[170:173], v[186:189], v[118:121]
	v_mfma_f32_16x16x32_bf16 v[110:113], v[178:181], v[186:189], v[110:113]
	v_mfma_f32_16x16x32_bf16 v[102:105], v[170:173], v[194:197], v[102:105]
	v_mfma_f32_16x16x32_bf16 v[94:97], v[178:181], v[194:197], v[94:97]
	v_mfma_f32_16x16x32_bf16 v[86:89], v[170:173], v[202:205], v[86:89]
	v_mfma_f32_16x16x32_bf16 v[78:81], v[178:181], v[202:205], v[78:81]
	v_mfma_f32_16x16x32_bf16 v[70:73], v[170:173], v[210:213], v[70:73]
	v_mfma_f32_16x16x32_bf16 v[66:69], v[178:181], v[210:213], v[66:69]
	v_mfma_f32_16x16x32_bf16 v[118:121], v[174:177], v[190:193], v[118:121]
	v_mfma_f32_16x16x32_bf16 v[110:113], v[182:185], v[190:193], v[110:113]
	v_mfma_f32_16x16x32_bf16 v[102:105], v[174:177], v[198:201], v[102:105]
	v_mfma_f32_16x16x32_bf16 v[94:97], v[182:185], v[198:201], v[94:97]
	v_mfma_f32_16x16x32_bf16 v[86:89], v[174:177], v[206:209], v[86:89]
	v_mfma_f32_16x16x32_bf16 v[78:81], v[182:185], v[206:209], v[78:81]
	v_mfma_f32_16x16x32_bf16 v[70:73], v[174:177], v[214:217], v[70:73]
	v_mfma_f32_16x16x32_bf16 v[66:69], v[182:185], v[214:217], v[66:69]
	s_setprio 0
	s_barrier
	s_add_i32 s6, s97, s31
	v_lshl_add_u64 v[146:147], v[146:147], 0, s[12:13]
	s_mov_b32 m0, s6
	ds_read_b128 v[186:189], v152 offset:49152
	ds_read_b128 v[190:193], v152 offset:50176
	ds_read_b128 v[194:197], v152 offset:51200
	ds_read_b128 v[198:201], v152 offset:52224
	ds_read_b128 v[202:205], v152 offset:53248
	ds_read_b128 v[206:209], v152 offset:54272
	ds_read_b128 v[210:213], v152 offset:55296
	ds_read_b128 v[214:217], v152 offset:56320
	global_load_lds_dwordx4 v[146:147], off
	s_add_i32 m0, s6, 0x2000
	s_add_u32 s6, s70, 0x20080
	v_lshl_add_u64 v[146:147], v[218:219], 0, s[12:13]
	s_addc_u32 s7, s71, 0
	s_add_i32 s70, vcc_lo, s31
	global_load_lds_dwordx4 v[146:147], off
	v_lshl_add_u64 v[146:147], s[6:7], 0, v[132:133]
	s_mov_b32 m0, s70
	s_nop 0
	global_load_lds_dwordx4 v[146:147], off
	v_lshl_add_u64 v[146:147], s[6:7], 0, v[136:137]
	s_add_i32 m0, s70, 0x2000
	s_nop 0
	global_load_lds_dwordx4 v[146:147], off
	v_lshl_add_u64 v[146:147], v[220:221], 0, s[12:13]
	s_mov_b32 m0, s82
	s_nop 0
	global_load_lds_dwordx4 v[146:147], off
	v_lshl_add_u64 v[146:147], v[222:223], 0, s[12:13]
	s_mov_b32 m0, s83
	s_nop 0
	global_load_lds_dwordx4 v[146:147], off
	s_waitcnt vmcnt(8)
	s_waitcnt lgkmcnt(0)
	s_barrier
	s_setprio 1
	s_waitcnt lgkmcnt(0)
	v_mfma_f32_16x16x32_bf16 v[62:65], v[154:157], v[186:189], v[62:65]
	v_mfma_f32_16x16x32_bf16 v[58:61], v[162:165], v[186:189], v[58:61]
	v_mfma_f32_16x16x32_bf16 v[50:53], v[154:157], v[194:197], v[50:53]
	v_mfma_f32_16x16x32_bf16 v[42:45], v[162:165], v[194:197], v[42:45]
	v_mfma_f32_16x16x32_bf16 v[34:37], v[154:157], v[202:205], v[34:37]
	v_mfma_f32_16x16x32_bf16 v[26:29], v[162:165], v[202:205], v[26:29]
	v_mfma_f32_16x16x32_bf16 v[18:21], v[154:157], v[210:213], v[18:21]
	v_mfma_f32_16x16x32_bf16 v[10:13], v[162:165], v[210:213], v[10:13]
	v_mfma_f32_16x16x32_bf16 v[62:65], v[158:161], v[190:193], v[62:65]
	v_mfma_f32_16x16x32_bf16 v[58:61], v[166:169], v[190:193], v[58:61]
	v_mfma_f32_16x16x32_bf16 v[50:53], v[158:161], v[198:201], v[50:53]
	v_mfma_f32_16x16x32_bf16 v[42:45], v[166:169], v[198:201], v[42:45]
	v_mfma_f32_16x16x32_bf16 v[34:37], v[158:161], v[206:209], v[34:37]
	v_mfma_f32_16x16x32_bf16 v[26:29], v[166:169], v[206:209], v[26:29]
	v_mfma_f32_16x16x32_bf16 v[18:21], v[158:161], v[214:217], v[18:21]
	v_mfma_f32_16x16x32_bf16 v[10:13], v[166:169], v[214:217], v[10:13]
	s_setprio 0
	s_setprio 1
	v_mfma_f32_16x16x32_bf16 v[54:57], v[170:173], v[186:189], v[54:57]
	v_mfma_f32_16x16x32_bf16 v[46:49], v[178:181], v[186:189], v[46:49]
	v_mfma_f32_16x16x32_bf16 v[38:41], v[170:173], v[194:197], v[38:41]
	v_mfma_f32_16x16x32_bf16 v[30:33], v[178:181], v[194:197], v[30:33]
	v_mfma_f32_16x16x32_bf16 v[22:25], v[170:173], v[202:205], v[22:25]
	v_mfma_f32_16x16x32_bf16 v[14:17], v[178:181], v[202:205], v[14:17]
	v_mfma_f32_16x16x32_bf16 v[6:9], v[170:173], v[210:213], v[6:9]
	v_mfma_f32_16x16x32_bf16 v[2:5], v[178:181], v[210:213], v[2:5]
	v_mfma_f32_16x16x32_bf16 v[54:57], v[174:177], v[190:193], v[54:57]
	v_mfma_f32_16x16x32_bf16 v[46:49], v[182:185], v[190:193], v[46:49]
	v_mfma_f32_16x16x32_bf16 v[38:41], v[174:177], v[198:201], v[38:41]
	v_mfma_f32_16x16x32_bf16 v[30:33], v[182:185], v[198:201], v[30:33]
	v_mfma_f32_16x16x32_bf16 v[22:25], v[174:177], v[206:209], v[22:25]
	v_mfma_f32_16x16x32_bf16 v[14:17], v[182:185], v[206:209], v[14:17]
	v_mfma_f32_16x16x32_bf16 v[6:9], v[174:177], v[214:217], v[6:9]
	v_mfma_f32_16x16x32_bf16 v[2:5], v[182:185], v[214:217], v[2:5]
	s_setprio 0
	s_add_i32 s96, s96, 2
	s_add_u32 s66, s66, 0x100
	s_addc_u32 s67, s67, 0
	s_add_u32 s94, s94, 0x100
	s_addc_u32 s95, s95, 0
	s_cmp_gt_u32 s96, 5
	s_barrier
	s_cbranch_scc0 .LBB0_560

.LBB0_584:
	ds_read_b128 v[154:157], v150
	ds_read_b128 v[158:161], v150 offset:1024
	ds_read_b128 v[162:165], v150 offset:2048
	ds_read_b128 v[166:169], v150 offset:3072
	ds_read_b128 v[170:173], v151
	ds_read_b128 v[174:177], v151 offset:1024
	ds_read_b128 v[178:181], v151 offset:2048
	ds_read_b128 v[182:185], v151 offset:3072
	v_lshl_add_u64 v[146:147], s[72:73], 0, v[138:139]
	s_add_i32 m0, s71, 0xc000
	ds_read_b128 v[186:189], v152
	ds_read_b128 v[190:193], v152 offset:1024
	ds_read_b128 v[194:197], v152 offset:2048
	ds_read_b128 v[198:201], v152 offset:3072
	ds_read_b128 v[202:205], v152 offset:4096
	ds_read_b128 v[206:209], v152 offset:5120
	ds_read_b128 v[210:213], v152 offset:6144
	ds_read_b128 v[214:217], v152 offset:7168
	global_load_lds_dwordx4 v[146:147], off
	v_lshl_add_u64 v[146:147], s[72:73], 0, v[140:141]
	s_add_i32 m0, s71, 0xe000
	s_nop 0
	global_load_lds_dwordx4 v[146:147], off
	s_add_u32 s6, s72, 0xfffe0080
	s_addc_u32 s7, s73, -1
	s_cmp_eq_u32 s94, 4
	s_cselect_b32 s77, s63, s7
	s_cselect_b32 s76, s90, s6
	s_cselect_b32 s75, s61, s93
	s_cselect_b32 s74, s91, s92
	s_waitcnt vmcnt(8)
	s_waitcnt lgkmcnt(0)
	s_barrier
	s_setprio 1
	s_waitcnt lgkmcnt(0)
	v_mfma_f32_16x16x32_bf16 v[126:129], v[154:157], v[186:189], v[126:129]
	v_mfma_f32_16x16x32_bf16 v[122:125], v[162:165], v[186:189], v[122:125]
	v_mfma_f32_16x16x32_bf16 v[110:113], v[154:157], v[194:197], v[110:113]
	v_mfma_f32_16x16x32_bf16 v[106:109], v[162:165], v[194:197], v[106:109]
	v_mfma_f32_16x16x32_bf16 v[94:97], v[154:157], v[202:205], v[94:97]
	v_mfma_f32_16x16x32_bf16 v[90:93], v[162:165], v[202:205], v[90:93]
	v_mfma_f32_16x16x32_bf16 v[78:81], v[154:157], v[210:213], v[78:81]
	v_mfma_f32_16x16x32_bf16 v[74:77], v[162:165], v[210:213], v[74:77]
	v_mfma_f32_16x16x32_bf16 v[126:129], v[158:161], v[190:193], v[126:129]
	v_mfma_f32_16x16x32_bf16 v[122:125], v[166:169], v[190:193], v[122:125]
	v_mfma_f32_16x16x32_bf16 v[110:113], v[158:161], v[198:201], v[110:113]
	v_mfma_f32_16x16x32_bf16 v[106:109], v[166:169], v[198:201], v[106:109]
	v_mfma_f32_16x16x32_bf16 v[94:97], v[158:161], v[206:209], v[94:97]
	v_mfma_f32_16x16x32_bf16 v[90:93], v[166:169], v[206:209], v[90:93]
	v_mfma_f32_16x16x32_bf16 v[78:81], v[158:161], v[214:217], v[78:81]
	v_mfma_f32_16x16x32_bf16 v[74:77], v[166:169], v[214:217], v[74:77]
	s_setprio 0
	s_setprio 1
	v_mfma_f32_16x16x32_bf16 v[118:121], v[170:173], v[186:189], v[118:121]
	v_mfma_f32_16x16x32_bf16 v[114:117], v[178:181], v[186:189], v[114:117]
	v_mfma_f32_16x16x32_bf16 v[102:105], v[170:173], v[194:197], v[102:105]
	v_mfma_f32_16x16x32_bf16 v[98:101], v[178:181], v[194:197], v[98:101]
	v_mfma_f32_16x16x32_bf16 v[86:89], v[170:173], v[202:205], v[86:89]
	v_mfma_f32_16x16x32_bf16 v[82:85], v[178:181], v[202:205], v[82:85]
	v_mfma_f32_16x16x32_bf16 v[70:73], v[170:173], v[210:213], v[70:73]
	v_mfma_f32_16x16x32_bf16 v[66:69], v[178:181], v[210:213], v[66:69]
	v_mfma_f32_16x16x32_bf16 v[118:121], v[174:177], v[190:193], v[118:121]
	v_mfma_f32_16x16x32_bf16 v[114:117], v[182:185], v[190:193], v[114:117]
	v_mfma_f32_16x16x32_bf16 v[102:105], v[174:177], v[198:201], v[102:105]
	v_mfma_f32_16x16x32_bf16 v[98:101], v[182:185], v[198:201], v[98:101]
	v_mfma_f32_16x16x32_bf16 v[86:89], v[174:177], v[206:209], v[86:89]
	v_mfma_f32_16x16x32_bf16 v[82:85], v[182:185], v[206:209], v[82:85]
	v_mfma_f32_16x16x32_bf16 v[70:73], v[174:177], v[214:217], v[70:73]
	v_mfma_f32_16x16x32_bf16 v[66:69], v[182:185], v[214:217], v[66:69]
	s_setprio 0
	s_barrier
	s_add_i32 s6, s87, s31
	v_lshl_add_u64 v[146:147], s[74:75], 0, v[132:133]
	s_mov_b32 m0, s6
	ds_read_b128 v[186:189], v152 offset:16384
	ds_read_b128 v[190:193], v152 offset:17408
	ds_read_b128 v[194:197], v152 offset:18432
	ds_read_b128 v[198:201], v152 offset:19456
	ds_read_b128 v[202:205], v152 offset:20480
	ds_read_b128 v[206:209], v152 offset:21504
	ds_read_b128 v[210:213], v152 offset:22528
	ds_read_b128 v[214:217], v152 offset:23552
	global_load_lds_dwordx4 v[146:147], off
	s_add_i32 m0, s6, 0x2000
	s_add_u32 s6, s74, 0x20000
	v_lshl_add_u64 v[218:219], s[74:75], 0, v[136:137]
	s_addc_u32 s7, s75, 0
	s_add_i32 s95, s88, s31
	global_load_lds_dwordx4 v[218:219], off
	v_lshl_add_u64 v[220:221], s[6:7], 0, v[132:133]
	s_mov_b32 m0, s95
	v_lshl_add_u64 v[222:223], s[76:77], 0, v[134:135]
	global_load_lds_dwordx4 v[220:221], off
	v_lshl_add_u64 v[220:221], s[6:7], 0, v[136:137]
	s_add_i32 m0, s95, 0x2000
	s_nop 0
	global_load_lds_dwordx4 v[220:221], off
	v_lshl_add_u64 v[220:221], s[76:77], 0, v[130:131]
	s_mov_b32 m0, s71
	s_nop 0
	global_load_lds_dwordx4 v[220:221], off
	s_mov_b32 m0, s78
	s_nop 0
	global_load_lds_dwordx4 v[222:223], off
	s_waitcnt vmcnt(8)
	s_waitcnt lgkmcnt(0)
	s_barrier
	s_setprio 1
	s_waitcnt lgkmcnt(0)
	v_mfma_f32_16x16x32_bf16 v[62:65], v[154:157], v[186:189], v[62:65]
	v_mfma_f32_16x16x32_bf16 v[58:61], v[162:165], v[186:189], v[58:61]
	v_mfma_f32_16x16x32_bf16 v[46:49], v[154:157], v[194:197], v[46:49]
	v_mfma_f32_16x16x32_bf16 v[42:45], v[162:165], v[194:197], v[42:45]
	v_mfma_f32_16x16x32_bf16 v[30:33], v[154:157], v[202:205], v[30:33]
	v_mfma_f32_16x16x32_bf16 v[26:29], v[162:165], v[202:205], v[26:29]
	v_mfma_f32_16x16x32_bf16 v[14:17], v[154:157], v[210:213], v[14:17]
	v_mfma_f32_16x16x32_bf16 v[10:13], v[162:165], v[210:213], v[10:13]
	v_mfma_f32_16x16x32_bf16 v[62:65], v[158:161], v[190:193], v[62:65]
	v_mfma_f32_16x16x32_bf16 v[58:61], v[166:169], v[190:193], v[58:61]
	v_mfma_f32_16x16x32_bf16 v[46:49], v[158:161], v[198:201], v[46:49]
	v_mfma_f32_16x16x32_bf16 v[42:45], v[166:169], v[198:201], v[42:45]
	v_mfma_f32_16x16x32_bf16 v[30:33], v[158:161], v[206:209], v[30:33]
	v_mfma_f32_16x16x32_bf16 v[26:29], v[166:169], v[206:209], v[26:29]
	v_mfma_f32_16x16x32_bf16 v[14:17], v[158:161], v[214:217], v[14:17]
	v_mfma_f32_16x16x32_bf16 v[10:13], v[166:169], v[214:217], v[10:13]
	s_setprio 0
	s_setprio 1
	v_mfma_f32_16x16x32_bf16 v[54:57], v[170:173], v[186:189], v[54:57]
	v_mfma_f32_16x16x32_bf16 v[50:53], v[178:181], v[186:189], v[50:53]
	v_mfma_f32_16x16x32_bf16 v[38:41], v[170:173], v[194:197], v[38:41]
	v_mfma_f32_16x16x32_bf16 v[34:37], v[178:181], v[194:197], v[34:37]
	v_mfma_f32_16x16x32_bf16 v[22:25], v[170:173], v[202:205], v[22:25]
	v_mfma_f32_16x16x32_bf16 v[18:21], v[178:181], v[202:205], v[18:21]
	v_mfma_f32_16x16x32_bf16 v[6:9], v[170:173], v[210:213], v[6:9]
	v_mfma_f32_16x16x32_bf16 v[2:5], v[178:181], v[210:213], v[2:5]
	v_mfma_f32_16x16x32_bf16 v[54:57], v[174:177], v[190:193], v[54:57]
	v_mfma_f32_16x16x32_bf16 v[50:53], v[182:185], v[190:193], v[50:53]
	v_mfma_f32_16x16x32_bf16 v[38:41], v[174:177], v[198:201], v[38:41]
	v_mfma_f32_16x16x32_bf16 v[34:37], v[182:185], v[198:201], v[34:37]
	v_mfma_f32_16x16x32_bf16 v[22:25], v[174:177], v[206:209], v[22:25]
	v_mfma_f32_16x16x32_bf16 v[18:21], v[182:185], v[206:209], v[18:21]
	v_mfma_f32_16x16x32_bf16 v[6:9], v[174:177], v[214:217], v[6:9]
	v_mfma_f32_16x16x32_bf16 v[2:5], v[182:185], v[214:217], v[2:5]
	s_setprio 0
	s_barrier
	s_add_i32 s95, 0, 0x18000
	v_add_u32_e32 v153, s95, v149
	s_add_i32 s96, 0, 0x1c000
	ds_read_b128 v[154:157], v153
	ds_read_b128 v[158:161], v153 offset:1024
	ds_read_b128 v[162:165], v153 offset:2048
	ds_read_b128 v[166:169], v153 offset:3072
	v_add_u32_e32 v153, s96, v149
	ds_read_b128 v[170:173], v153
	ds_read_b128 v[174:177], v153 offset:1024
	ds_read_b128 v[178:181], v153 offset:2048
	ds_read_b128 v[182:185], v153 offset:3072
	s_add_u32 s6, s76, 0x20000
	s_addc_u32 s7, s77, 0
	s_mov_b32 m0, s79
	v_lshl_add_u64 v[224:225], s[6:7], 0, v[130:131]
	ds_read_b128 v[186:189], v152 offset:32768
	ds_read_b128 v[190:193], v152 offset:33792
	ds_read_b128 v[194:197], v152 offset:34816
	ds_read_b128 v[198:201], v152 offset:35840
	ds_read_b128 v[202:205], v152 offset:36864
	ds_read_b128 v[206:209], v152 offset:37888
	ds_read_b128 v[210:213], v152 offset:38912
	ds_read_b128 v[214:217], v152 offset:39936
	global_load_lds_dwordx4 v[224:225], off
	v_lshl_add_u64 v[224:225], s[6:7], 0, v[134:135]
	s_mov_b32 m0, s80
	s_nop 0
	global_load_lds_dwordx4 v[224:225], off
	s_waitcnt vmcnt(8)
	s_waitcnt lgkmcnt(0)
	s_barrier
	s_setprio 1
	s_waitcnt lgkmcnt(0)
	v_mfma_f32_16x16x32_bf16 v[126:129], v[154:157], v[186:189], v[126:129]
	v_mfma_f32_16x16x32_bf16 v[122:125], v[162:165], v[186:189], v[122:125]
	v_mfma_f32_16x16x32_bf16 v[110:113], v[154:157], v[194:197], v[110:113]
	v_mfma_f32_16x16x32_bf16 v[106:109], v[162:165], v[194:197], v[106:109]
	v_mfma_f32_16x16x32_bf16 v[94:97], v[154:157], v[202:205], v[94:97]
	v_mfma_f32_16x16x32_bf16 v[90:93], v[162:165], v[202:205], v[90:93]
	v_mfma_f32_16x16x32_bf16 v[78:81], v[154:157], v[210:213], v[78:81]
	v_mfma_f32_16x16x32_bf16 v[74:77], v[162:165], v[210:213], v[74:77]
	v_mfma_f32_16x16x32_bf16 v[126:129], v[158:161], v[190:193], v[126:129]
	v_mfma_f32_16x16x32_bf16 v[122:125], v[166:169], v[190:193], v[122:125]
	v_mfma_f32_16x16x32_bf16 v[110:113], v[158:161], v[198:201], v[110:113]
	v_mfma_f32_16x16x32_bf16 v[106:109], v[166:169], v[198:201], v[106:109]
	v_mfma_f32_16x16x32_bf16 v[94:97], v[158:161], v[206:209], v[94:97]
	v_mfma_f32_16x16x32_bf16 v[90:93], v[166:169], v[206:209], v[90:93]
	v_mfma_f32_16x16x32_bf16 v[78:81], v[158:161], v[214:217], v[78:81]
	v_mfma_f32_16x16x32_bf16 v[74:77], v[166:169], v[214:217], v[74:77]
	s_setprio 0
	s_setprio 1
	v_mfma_f32_16x16x32_bf16 v[118:121], v[170:173], v[186:189], v[118:121]
	v_mfma_f32_16x16x32_bf16 v[114:117], v[178:181], v[186:189], v[114:117]
	v_mfma_f32_16x16x32_bf16 v[102:105], v[170:173], v[194:197], v[102:105]
	v_mfma_f32_16x16x32_bf16 v[98:101], v[178:181], v[194:197], v[98:101]
	v_mfma_f32_16x16x32_bf16 v[86:89], v[170:173], v[202:205], v[86:89]
	v_mfma_f32_16x16x32_bf16 v[82:85], v[178:181], v[202:205], v[82:85]
	v_mfma_f32_16x16x32_bf16 v[70:73], v[170:173], v[210:213], v[70:73]
	v_mfma_f32_16x16x32_bf16 v[66:69], v[178:181], v[210:213], v[66:69]
	v_mfma_f32_16x16x32_bf16 v[118:121], v[174:177], v[190:193], v[118:121]
	v_mfma_f32_16x16x32_bf16 v[114:117], v[182:185], v[190:193], v[114:117]
	v_mfma_f32_16x16x32_bf16 v[102:105], v[174:177], v[198:201], v[102:105]
	v_mfma_f32_16x16x32_bf16 v[98:101], v[182:185], v[198:201], v[98:101]
	v_mfma_f32_16x16x32_bf16 v[86:89], v[174:177], v[206:209], v[86:89]
	v_mfma_f32_16x16x32_bf16 v[82:85], v[182:185], v[206:209], v[82:85]
	v_mfma_f32_16x16x32_bf16 v[70:73], v[174:177], v[214:217], v[70:73]
	v_mfma_f32_16x16x32_bf16 v[66:69], v[182:185], v[214:217], v[66:69]
	s_setprio 0
	s_barrier
	s_add_i32 s6, s95, s31
	v_lshl_add_u64 v[146:147], v[146:147], 0, s[20:21]
	s_mov_b32 m0, s6
	ds_read_b128 v[186:189], v152 offset:49152
	ds_read_b128 v[190:193], v152 offset:50176
	ds_read_b128 v[194:197], v152 offset:51200
	ds_read_b128 v[198:201], v152 offset:52224
	ds_read_b128 v[202:205], v152 offset:53248
	ds_read_b128 v[206:209], v152 offset:54272
	ds_read_b128 v[210:213], v152 offset:55296
	ds_read_b128 v[214:217], v152 offset:56320
	global_load_lds_dwordx4 v[146:147], off
	s_add_i32 m0, s6, 0x2000
	s_add_u32 s6, s74, 0x20080
	v_lshl_add_u64 v[146:147], v[218:219], 0, s[20:21]
	s_addc_u32 s7, s75, 0
	s_add_i32 s74, s96, s31
	global_load_lds_dwordx4 v[146:147], off
	v_lshl_add_u64 v[146:147], s[6:7], 0, v[132:133]
	s_mov_b32 m0, s74
	s_nop 0
	global_load_lds_dwordx4 v[146:147], off
	v_lshl_add_u64 v[146:147], s[6:7], 0, v[136:137]
	s_add_i32 m0, s74, 0x2000
	s_nop 0
	global_load_lds_dwordx4 v[146:147], off
	v_lshl_add_u64 v[146:147], v[220:221], 0, s[20:21]
	s_mov_b32 m0, s84
	s_nop 0
	global_load_lds_dwordx4 v[146:147], off
	v_lshl_add_u64 v[146:147], v[222:223], 0, s[20:21]
	s_mov_b32 m0, s85
	s_nop 0
	global_load_lds_dwordx4 v[146:147], off
	s_waitcnt vmcnt(8)
	s_waitcnt lgkmcnt(0)
	s_barrier
	s_setprio 1
	s_waitcnt lgkmcnt(0)
	v_mfma_f32_16x16x32_bf16 v[62:65], v[154:157], v[186:189], v[62:65]
	v_mfma_f32_16x16x32_bf16 v[58:61], v[162:165], v[186:189], v[58:61]
	v_mfma_f32_16x16x32_bf16 v[46:49], v[154:157], v[194:197], v[46:49]
	v_mfma_f32_16x16x32_bf16 v[42:45], v[162:165], v[194:197], v[42:45]
	v_mfma_f32_16x16x32_bf16 v[30:33], v[154:157], v[202:205], v[30:33]
	v_mfma_f32_16x16x32_bf16 v[26:29], v[162:165], v[202:205], v[26:29]
	v_mfma_f32_16x16x32_bf16 v[14:17], v[154:157], v[210:213], v[14:17]
	v_mfma_f32_16x16x32_bf16 v[10:13], v[162:165], v[210:213], v[10:13]
	v_mfma_f32_16x16x32_bf16 v[62:65], v[158:161], v[190:193], v[62:65]
	v_mfma_f32_16x16x32_bf16 v[58:61], v[166:169], v[190:193], v[58:61]
	v_mfma_f32_16x16x32_bf16 v[46:49], v[158:161], v[198:201], v[46:49]
	v_mfma_f32_16x16x32_bf16 v[42:45], v[166:169], v[198:201], v[42:45]
	v_mfma_f32_16x16x32_bf16 v[30:33], v[158:161], v[206:209], v[30:33]
	v_mfma_f32_16x16x32_bf16 v[26:29], v[166:169], v[206:209], v[26:29]
	v_mfma_f32_16x16x32_bf16 v[14:17], v[158:161], v[214:217], v[14:17]
	v_mfma_f32_16x16x32_bf16 v[10:13], v[166:169], v[214:217], v[10:13]
	s_setprio 0
	s_setprio 1
	v_mfma_f32_16x16x32_bf16 v[54:57], v[170:173], v[186:189], v[54:57]
	v_mfma_f32_16x16x32_bf16 v[50:53], v[178:181], v[186:189], v[50:53]
	v_mfma_f32_16x16x32_bf16 v[38:41], v[170:173], v[194:197], v[38:41]
	v_mfma_f32_16x16x32_bf16 v[34:37], v[178:181], v[194:197], v[34:37]
	v_mfma_f32_16x16x32_bf16 v[22:25], v[170:173], v[202:205], v[22:25]
	v_mfma_f32_16x16x32_bf16 v[18:21], v[178:181], v[202:205], v[18:21]
	v_mfma_f32_16x16x32_bf16 v[6:9], v[170:173], v[210:213], v[6:9]
	v_mfma_f32_16x16x32_bf16 v[2:5], v[178:181], v[210:213], v[2:5]
	v_mfma_f32_16x16x32_bf16 v[54:57], v[174:177], v[190:193], v[54:57]
	v_mfma_f32_16x16x32_bf16 v[50:53], v[182:185], v[190:193], v[50:53]
	v_mfma_f32_16x16x32_bf16 v[38:41], v[174:177], v[198:201], v[38:41]
	v_mfma_f32_16x16x32_bf16 v[34:37], v[182:185], v[198:201], v[34:37]
	v_mfma_f32_16x16x32_bf16 v[22:25], v[174:177], v[206:209], v[22:25]
	v_mfma_f32_16x16x32_bf16 v[18:21], v[182:185], v[206:209], v[18:21]
	v_mfma_f32_16x16x32_bf16 v[6:9], v[174:177], v[214:217], v[6:9]
	v_mfma_f32_16x16x32_bf16 v[2:5], v[182:185], v[214:217], v[2:5]
	s_setprio 0
	s_add_i32 s94, s94, 2
	s_add_u32 s72, s72, 0x100
	s_addc_u32 s73, s73, 0
	s_add_u32 s92, s92, 0x100
	s_addc_u32 s93, s93, 0
	s_cmp_gt_u32 s94, 5
	s_barrier
	s_cbranch_scc0 .LBB0_584

.LBB0_662:
	ds_read_b128 v[130:133], v231
	ds_read_b128 v[134:137], v231 offset:1024
	ds_read_b128 v[138:141], v231 offset:2048
	ds_read_b128 v[142:145], v231 offset:3072
	ds_read_b128 v[146:149], v232
	ds_read_b128 v[150:153], v232 offset:1024
	ds_read_b128 v[154:157], v232 offset:2048
	ds_read_b128 v[158:161], v232 offset:3072
	v_lshl_add_u64 v[208:209], s[0:1], 0, v[198:199]
	s_add_i32 m0, s77, 0xc000
	ds_read_b128 v[162:165], v233
	ds_read_b128 v[166:169], v233 offset:1024
	ds_read_b128 v[170:173], v233 offset:2048
	ds_read_b128 v[174:177], v233 offset:3072
	ds_read_b128 v[178:181], v233 offset:4096
	ds_read_b128 v[182:185], v233 offset:5120
	ds_read_b128 v[186:189], v233 offset:6144
	ds_read_b128 v[190:193], v233 offset:7168
	global_load_lds_dwordx4 v[208:209], off
	v_lshl_add_u64 v[208:209], s[0:1], 0, v[200:201]
	s_add_i32 m0, s77, 0xe000
	s_nop 0
	global_load_lds_dwordx4 v[208:209], off
	s_add_u32 s6, s0, 0xfffc0080
	s_addc_u32 s7, s1, -1
	s_cmp_eq_u32 s67, 12
	s_cselect_b32 s11, s31, s7
	s_cselect_b32 s10, s57, s6
	s_cselect_b32 s9, s55, s66
	s_cselect_b32 s8, s63, s65
	s_waitcnt vmcnt(8)
	s_waitcnt lgkmcnt(0)
	s_barrier
	s_setprio 1
	s_waitcnt lgkmcnt(0)
	v_mfma_f32_16x16x32_bf16 v[126:129], v[130:133], v[162:165], v[126:129]
	v_mfma_f32_16x16x32_bf16 v[122:125], v[138:141], v[162:165], v[122:125]
	v_mfma_f32_16x16x32_bf16 v[110:113], v[130:133], v[170:173], v[110:113]
	v_mfma_f32_16x16x32_bf16 v[106:109], v[138:141], v[170:173], v[106:109]
	v_mfma_f32_16x16x32_bf16 v[94:97], v[130:133], v[178:181], v[94:97]
	v_mfma_f32_16x16x32_bf16 v[90:93], v[138:141], v[178:181], v[90:93]
	v_mfma_f32_16x16x32_bf16 v[78:81], v[130:133], v[186:189], v[78:81]
	v_mfma_f32_16x16x32_bf16 v[74:77], v[138:141], v[186:189], v[74:77]
	v_mfma_f32_16x16x32_bf16 v[126:129], v[134:137], v[166:169], v[126:129]
	v_mfma_f32_16x16x32_bf16 v[122:125], v[142:145], v[166:169], v[122:125]
	v_mfma_f32_16x16x32_bf16 v[110:113], v[134:137], v[174:177], v[110:113]
	v_mfma_f32_16x16x32_bf16 v[106:109], v[142:145], v[174:177], v[106:109]
	v_mfma_f32_16x16x32_bf16 v[94:97], v[134:137], v[182:185], v[94:97]
	v_mfma_f32_16x16x32_bf16 v[90:93], v[142:145], v[182:185], v[90:93]
	v_mfma_f32_16x16x32_bf16 v[78:81], v[134:137], v[190:193], v[78:81]
	v_mfma_f32_16x16x32_bf16 v[74:77], v[142:145], v[190:193], v[74:77]
	s_setprio 0
	s_setprio 1
	v_mfma_f32_16x16x32_bf16 v[118:121], v[146:149], v[162:165], v[118:121]
	v_mfma_f32_16x16x32_bf16 v[114:117], v[154:157], v[162:165], v[114:117]
	v_mfma_f32_16x16x32_bf16 v[102:105], v[146:149], v[170:173], v[102:105]
	v_mfma_f32_16x16x32_bf16 v[98:101], v[154:157], v[170:173], v[98:101]
	v_mfma_f32_16x16x32_bf16 v[86:89], v[146:149], v[178:181], v[86:89]
	v_mfma_f32_16x16x32_bf16 v[82:85], v[154:157], v[178:181], v[82:85]
	v_mfma_f32_16x16x32_bf16 v[70:73], v[146:149], v[186:189], v[70:73]
	v_mfma_f32_16x16x32_bf16 v[66:69], v[154:157], v[186:189], v[66:69]
	v_mfma_f32_16x16x32_bf16 v[118:121], v[150:153], v[166:169], v[118:121]
	v_mfma_f32_16x16x32_bf16 v[114:117], v[158:161], v[166:169], v[114:117]
	v_mfma_f32_16x16x32_bf16 v[102:105], v[150:153], v[174:177], v[102:105]
	v_mfma_f32_16x16x32_bf16 v[98:101], v[158:161], v[174:177], v[98:101]
	v_mfma_f32_16x16x32_bf16 v[86:89], v[150:153], v[182:185], v[86:89]
	v_mfma_f32_16x16x32_bf16 v[82:85], v[158:161], v[182:185], v[82:85]
	v_mfma_f32_16x16x32_bf16 v[70:73], v[150:153], v[190:193], v[70:73]
	v_mfma_f32_16x16x32_bf16 v[66:69], v[158:161], v[190:193], v[66:69]
	s_setprio 0
	s_barrier
	s_add_i32 s6, s94, s76
	v_lshl_add_u64 v[208:209], s[8:9], 0, v[194:195]
	s_mov_b32 m0, s6
	ds_read_b128 v[162:165], v233 offset:16384
	ds_read_b128 v[166:169], v233 offset:17408
	ds_read_b128 v[170:173], v233 offset:18432
	ds_read_b128 v[174:177], v233 offset:19456
	ds_read_b128 v[178:181], v233 offset:20480
	ds_read_b128 v[182:185], v233 offset:21504
	ds_read_b128 v[186:189], v233 offset:22528
	ds_read_b128 v[190:193], v233 offset:23552
	global_load_lds_dwordx4 v[208:209], off
	s_add_i32 m0, s6, 0x2000
	s_add_u32 s6, s8, 0x40000
	v_lshl_add_u64 v[210:211], s[8:9], 0, v[196:197]
	s_addc_u32 s7, s9, 0
	s_add_i32 s70, s95, s76
	global_load_lds_dwordx4 v[210:211], off
	v_lshl_add_u64 v[212:213], s[6:7], 0, v[194:195]
	s_mov_b32 m0, s70
	v_lshl_add_u64 v[214:215], s[10:11], 0, v[196:197]
	global_load_lds_dwordx4 v[212:213], off
	v_lshl_add_u64 v[212:213], s[6:7], 0, v[196:197]
	s_add_i32 m0, s70, 0x2000
	s_nop 0
	global_load_lds_dwordx4 v[212:213], off
	v_lshl_add_u64 v[212:213], s[10:11], 0, v[194:195]
	s_mov_b32 m0, s77
	s_nop 0
	global_load_lds_dwordx4 v[212:213], off
	s_mov_b32 m0, s78
	s_nop 0
	global_load_lds_dwordx4 v[214:215], off
	s_waitcnt vmcnt(8)
	s_waitcnt lgkmcnt(0)
	s_barrier
	s_setprio 1
	s_waitcnt lgkmcnt(0)
	v_mfma_f32_16x16x32_bf16 v[58:61], v[130:133], v[162:165], v[58:61]
	v_mfma_f32_16x16x32_bf16 v[62:65], v[138:141], v[162:165], v[62:65]
	v_mfma_f32_16x16x32_bf16 v[46:49], v[130:133], v[170:173], v[46:49]
	v_mfma_f32_16x16x32_bf16 v[42:45], v[138:141], v[170:173], v[42:45]
	v_mfma_f32_16x16x32_bf16 v[30:33], v[130:133], v[178:181], v[30:33]
	v_mfma_f32_16x16x32_bf16 v[26:29], v[138:141], v[178:181], v[26:29]
	v_mfma_f32_16x16x32_bf16 v[14:17], v[130:133], v[186:189], v[14:17]
	v_mfma_f32_16x16x32_bf16 v[10:13], v[138:141], v[186:189], v[10:13]
	v_mfma_f32_16x16x32_bf16 v[58:61], v[134:137], v[166:169], v[58:61]
	v_mfma_f32_16x16x32_bf16 v[62:65], v[142:145], v[166:169], v[62:65]
	v_mfma_f32_16x16x32_bf16 v[46:49], v[134:137], v[174:177], v[46:49]
	v_mfma_f32_16x16x32_bf16 v[42:45], v[142:145], v[174:177], v[42:45]
	v_mfma_f32_16x16x32_bf16 v[30:33], v[134:137], v[182:185], v[30:33]
	v_mfma_f32_16x16x32_bf16 v[26:29], v[142:145], v[182:185], v[26:29]
	v_mfma_f32_16x16x32_bf16 v[14:17], v[134:137], v[190:193], v[14:17]
	v_mfma_f32_16x16x32_bf16 v[10:13], v[142:145], v[190:193], v[10:13]
	s_setprio 0
	s_setprio 1
	v_mfma_f32_16x16x32_bf16 v[54:57], v[146:149], v[162:165], v[54:57]
	v_mfma_f32_16x16x32_bf16 v[50:53], v[154:157], v[162:165], v[50:53]
	v_mfma_f32_16x16x32_bf16 v[38:41], v[146:149], v[170:173], v[38:41]
	v_mfma_f32_16x16x32_bf16 v[34:37], v[154:157], v[170:173], v[34:37]
	v_mfma_f32_16x16x32_bf16 v[22:25], v[146:149], v[178:181], v[22:25]
	v_mfma_f32_16x16x32_bf16 v[18:21], v[154:157], v[178:181], v[18:21]
	v_mfma_f32_16x16x32_bf16 v[6:9], v[146:149], v[186:189], v[6:9]
	v_mfma_f32_16x16x32_bf16 v[2:5], v[154:157], v[186:189], v[2:5]
	v_mfma_f32_16x16x32_bf16 v[54:57], v[150:153], v[166:169], v[54:57]
	v_mfma_f32_16x16x32_bf16 v[50:53], v[158:161], v[166:169], v[50:53]
	v_mfma_f32_16x16x32_bf16 v[38:41], v[150:153], v[174:177], v[38:41]
	v_mfma_f32_16x16x32_bf16 v[34:37], v[158:161], v[174:177], v[34:37]
	v_mfma_f32_16x16x32_bf16 v[22:25], v[150:153], v[182:185], v[22:25]
	v_mfma_f32_16x16x32_bf16 v[18:21], v[158:161], v[182:185], v[18:21]
	v_mfma_f32_16x16x32_bf16 v[6:9], v[150:153], v[190:193], v[6:9]
	v_mfma_f32_16x16x32_bf16 v[2:5], v[158:161], v[190:193], v[2:5]
	s_setprio 0
	s_barrier
	s_add_i32 s70, 0, 0x18000
	s_add_i32 s71, 0, 0x1c000
	v_add_u32_e32 v142, s70, v230
	v_add_u32_e32 v158, s71, v230
	ds_read_b128 v[130:133], v142
	ds_read_b128 v[134:137], v142 offset:1024
	ds_read_b128 v[138:141], v142 offset:2048
	ds_read_b128 v[142:145], v142 offset:3072
	ds_read_b128 v[146:149], v158
	ds_read_b128 v[150:153], v158 offset:1024
	ds_read_b128 v[154:157], v158 offset:2048
	ds_read_b128 v[158:161], v158 offset:3072
	s_add_u32 s6, s10, 0x40000
	s_addc_u32 s7, s11, 0
	s_mov_b32 m0, s79
	v_lshl_add_u64 v[216:217], s[6:7], 0, v[194:195]
	ds_read_b128 v[162:165], v233 offset:32768
	ds_read_b128 v[166:169], v233 offset:33792
	ds_read_b128 v[170:173], v233 offset:34816
	ds_read_b128 v[174:177], v233 offset:35840
	ds_read_b128 v[178:181], v233 offset:36864
	ds_read_b128 v[182:185], v233 offset:37888
	ds_read_b128 v[186:189], v233 offset:38912
	ds_read_b128 v[190:193], v233 offset:39936
	global_load_lds_dwordx4 v[216:217], off
	v_lshl_add_u64 v[216:217], s[6:7], 0, v[196:197]
	s_mov_b32 m0, s80
	s_nop 0
	global_load_lds_dwordx4 v[216:217], off
	s_waitcnt vmcnt(8)
	s_waitcnt lgkmcnt(0)
	s_barrier
	s_setprio 1
	s_waitcnt lgkmcnt(0)
	v_mfma_f32_16x16x32_bf16 v[126:129], v[130:133], v[162:165], v[126:129]
	v_mfma_f32_16x16x32_bf16 v[122:125], v[138:141], v[162:165], v[122:125]
	v_mfma_f32_16x16x32_bf16 v[110:113], v[130:133], v[170:173], v[110:113]
	v_mfma_f32_16x16x32_bf16 v[106:109], v[138:141], v[170:173], v[106:109]
	v_mfma_f32_16x16x32_bf16 v[94:97], v[130:133], v[178:181], v[94:97]
	v_mfma_f32_16x16x32_bf16 v[90:93], v[138:141], v[178:181], v[90:93]
	v_mfma_f32_16x16x32_bf16 v[78:81], v[130:133], v[186:189], v[78:81]
	v_mfma_f32_16x16x32_bf16 v[74:77], v[138:141], v[186:189], v[74:77]
	v_mfma_f32_16x16x32_bf16 v[126:129], v[134:137], v[166:169], v[126:129]
	v_mfma_f32_16x16x32_bf16 v[122:125], v[142:145], v[166:169], v[122:125]
	v_mfma_f32_16x16x32_bf16 v[110:113], v[134:137], v[174:177], v[110:113]
	v_mfma_f32_16x16x32_bf16 v[106:109], v[142:145], v[174:177], v[106:109]
	v_mfma_f32_16x16x32_bf16 v[94:97], v[134:137], v[182:185], v[94:97]
	v_mfma_f32_16x16x32_bf16 v[90:93], v[142:145], v[182:185], v[90:93]
	v_mfma_f32_16x16x32_bf16 v[78:81], v[134:137], v[190:193], v[78:81]
	v_mfma_f32_16x16x32_bf16 v[74:77], v[142:145], v[190:193], v[74:77]
	s_setprio 0
	s_setprio 1
	v_mfma_f32_16x16x32_bf16 v[118:121], v[146:149], v[162:165], v[118:121]
	v_mfma_f32_16x16x32_bf16 v[114:117], v[154:157], v[162:165], v[114:117]
	v_mfma_f32_16x16x32_bf16 v[102:105], v[146:149], v[170:173], v[102:105]
	v_mfma_f32_16x16x32_bf16 v[98:101], v[154:157], v[170:173], v[98:101]
	v_mfma_f32_16x16x32_bf16 v[86:89], v[146:149], v[178:181], v[86:89]
	v_mfma_f32_16x16x32_bf16 v[82:85], v[154:157], v[178:181], v[82:85]
	v_mfma_f32_16x16x32_bf16 v[70:73], v[146:149], v[186:189], v[70:73]
	v_mfma_f32_16x16x32_bf16 v[66:69], v[154:157], v[186:189], v[66:69]
	v_mfma_f32_16x16x32_bf16 v[118:121], v[150:153], v[166:169], v[118:121]
	v_mfma_f32_16x16x32_bf16 v[114:117], v[158:161], v[166:169], v[114:117]
	v_mfma_f32_16x16x32_bf16 v[102:105], v[150:153], v[174:177], v[102:105]
	v_mfma_f32_16x16x32_bf16 v[98:101], v[158:161], v[174:177], v[98:101]
	v_mfma_f32_16x16x32_bf16 v[86:89], v[150:153], v[182:185], v[86:89]
	v_mfma_f32_16x16x32_bf16 v[82:85], v[158:161], v[182:185], v[82:85]
	v_mfma_f32_16x16x32_bf16 v[70:73], v[150:153], v[190:193], v[70:73]
	v_mfma_f32_16x16x32_bf16 v[66:69], v[158:161], v[190:193], v[66:69]
	s_setprio 0
	s_barrier
	s_add_i32 s6, s70, s76
	v_lshl_add_u64 v[208:209], v[208:209], 0, s[50:51]
	s_mov_b32 m0, s6
	ds_read_b128 v[162:165], v233 offset:49152
	ds_read_b128 v[166:169], v233 offset:50176
	ds_read_b128 v[170:173], v233 offset:51200
	ds_read_b128 v[174:177], v233 offset:52224
	ds_read_b128 v[178:181], v233 offset:53248
	ds_read_b128 v[182:185], v233 offset:54272
	ds_read_b128 v[186:189], v233 offset:55296
	ds_read_b128 v[190:193], v233 offset:56320
	global_load_lds_dwordx4 v[208:209], off
	s_add_i32 m0, s6, 0x2000
	s_add_u32 s6, s8, 0x40080
	v_lshl_add_u64 v[208:209], v[210:211], 0, s[50:51]
	s_addc_u32 s7, s9, 0
	s_add_i32 s8, s71, s76
	global_load_lds_dwordx4 v[208:209], off
	v_lshl_add_u64 v[208:209], s[6:7], 0, v[194:195]
	s_mov_b32 m0, s8
	s_nop 0
	global_load_lds_dwordx4 v[208:209], off
	v_lshl_add_u64 v[208:209], s[6:7], 0, v[196:197]
	s_add_i32 m0, s8, 0x2000
	s_nop 0
	global_load_lds_dwordx4 v[208:209], off
	v_lshl_add_u64 v[208:209], v[212:213], 0, s[50:51]
	s_mov_b32 m0, s86
	s_nop 0
	global_load_lds_dwordx4 v[208:209], off
	v_lshl_add_u64 v[208:209], v[214:215], 0, s[50:51]
	s_mov_b32 m0, s87
	s_nop 0
	global_load_lds_dwordx4 v[208:209], off
	s_waitcnt vmcnt(8)
	s_waitcnt lgkmcnt(0)
	s_barrier
	s_setprio 1
	s_waitcnt lgkmcnt(0)
	v_mfma_f32_16x16x32_bf16 v[58:61], v[130:133], v[162:165], v[58:61]
	v_mfma_f32_16x16x32_bf16 v[62:65], v[138:141], v[162:165], v[62:65]
	v_mfma_f32_16x16x32_bf16 v[46:49], v[130:133], v[170:173], v[46:49]
	v_mfma_f32_16x16x32_bf16 v[42:45], v[138:141], v[170:173], v[42:45]
	v_mfma_f32_16x16x32_bf16 v[30:33], v[130:133], v[178:181], v[30:33]
	v_mfma_f32_16x16x32_bf16 v[26:29], v[138:141], v[178:181], v[26:29]
	v_mfma_f32_16x16x32_bf16 v[14:17], v[130:133], v[186:189], v[14:17]
	v_mfma_f32_16x16x32_bf16 v[10:13], v[138:141], v[186:189], v[10:13]
	v_mfma_f32_16x16x32_bf16 v[58:61], v[134:137], v[166:169], v[58:61]
	v_mfma_f32_16x16x32_bf16 v[62:65], v[142:145], v[166:169], v[62:65]
	v_mfma_f32_16x16x32_bf16 v[46:49], v[134:137], v[174:177], v[46:49]
	v_mfma_f32_16x16x32_bf16 v[42:45], v[142:145], v[174:177], v[42:45]
	v_mfma_f32_16x16x32_bf16 v[30:33], v[134:137], v[182:185], v[30:33]
	v_mfma_f32_16x16x32_bf16 v[26:29], v[142:145], v[182:185], v[26:29]
	v_mfma_f32_16x16x32_bf16 v[14:17], v[134:137], v[190:193], v[14:17]
	v_mfma_f32_16x16x32_bf16 v[10:13], v[142:145], v[190:193], v[10:13]
	s_setprio 0
	s_setprio 1
	v_mfma_f32_16x16x32_bf16 v[54:57], v[146:149], v[162:165], v[54:57]
	v_mfma_f32_16x16x32_bf16 v[50:53], v[154:157], v[162:165], v[50:53]
	v_mfma_f32_16x16x32_bf16 v[38:41], v[146:149], v[170:173], v[38:41]
	v_mfma_f32_16x16x32_bf16 v[34:37], v[154:157], v[170:173], v[34:37]
	v_mfma_f32_16x16x32_bf16 v[22:25], v[146:149], v[178:181], v[22:25]
	v_mfma_f32_16x16x32_bf16 v[18:21], v[154:157], v[178:181], v[18:21]
	v_mfma_f32_16x16x32_bf16 v[6:9], v[146:149], v[186:189], v[6:9]
	v_mfma_f32_16x16x32_bf16 v[2:5], v[154:157], v[186:189], v[2:5]
	v_mfma_f32_16x16x32_bf16 v[54:57], v[150:153], v[166:169], v[54:57]
	v_mfma_f32_16x16x32_bf16 v[50:53], v[158:161], v[166:169], v[50:53]
	v_mfma_f32_16x16x32_bf16 v[38:41], v[150:153], v[174:177], v[38:41]
	v_mfma_f32_16x16x32_bf16 v[34:37], v[158:161], v[174:177], v[34:37]
	v_mfma_f32_16x16x32_bf16 v[22:25], v[150:153], v[182:185], v[22:25]
	v_mfma_f32_16x16x32_bf16 v[18:21], v[158:161], v[182:185], v[18:21]
	v_mfma_f32_16x16x32_bf16 v[6:9], v[150:153], v[190:193], v[6:9]
	v_mfma_f32_16x16x32_bf16 v[2:5], v[158:161], v[190:193], v[2:5]
	s_setprio 0
	s_add_i32 s67, s67, 2
	s_add_u32 s0, s0, 0x100
	s_addc_u32 s1, s1, 0
	s_add_u32 s65, s65, 0x100
	s_addc_u32 s66, s66, 0
	s_cmp_gt_u32 s67, 13
	s_barrier
	s_cbranch_scc0 .LBB0_662

.LBB0_780:
	ds_read_b128 v[156:159], v152
	ds_read_b128 v[160:163], v152 offset:1024
	ds_read_b128 v[164:167], v152 offset:2048
	ds_read_b128 v[168:171], v152 offset:3072
	ds_read_b128 v[172:175], v153
	ds_read_b128 v[176:179], v153 offset:1024
	ds_read_b128 v[180:183], v153 offset:2048
	ds_read_b128 v[184:187], v153 offset:3072
	v_lshl_add_u64 v[148:149], s[48:49], 0, v[140:141]
	s_add_i32 m0, s54, 0xc000
	ds_read_b128 v[188:191], v154
	ds_read_b128 v[192:195], v154 offset:1024
	ds_read_b128 v[196:199], v154 offset:2048
	ds_read_b128 v[200:203], v154 offset:3072
	ds_read_b128 v[204:207], v154 offset:4096
	ds_read_b128 v[208:211], v154 offset:5120
	ds_read_b128 v[212:215], v154 offset:6144
	ds_read_b128 v[216:219], v154 offset:7168
	global_load_lds_dwordx4 v[148:149], off
	v_lshl_add_u64 v[148:149], s[48:49], 0, v[142:143]
	s_add_i32 m0, s54, 0xe000
	s_nop 0
	global_load_lds_dwordx4 v[148:149], off
	s_add_u32 s6, s48, 0xfffc0080
	s_addc_u32 s7, s49, -1
	s_cmp_eq_u32 s82, 12
	s_cselect_b32 s53, s43, s7
	s_cselect_b32 s52, s78, s6
	s_cselect_b32 s51, s39, s81
	s_cselect_b32 s50, s79, s80
	s_waitcnt vmcnt(8)
	s_waitcnt lgkmcnt(0)
	s_barrier
	s_setprio 1
	s_waitcnt lgkmcnt(0)
	v_mfma_f32_16x16x32_bf16 v[126:129], v[156:159], v[188:191], v[126:129]
	v_mfma_f32_16x16x32_bf16 v[122:125], v[164:167], v[188:191], v[122:125]
	v_mfma_f32_16x16x32_bf16 v[110:113], v[156:159], v[196:199], v[110:113]
	v_mfma_f32_16x16x32_bf16 v[106:109], v[164:167], v[196:199], v[106:109]
	v_mfma_f32_16x16x32_bf16 v[94:97], v[156:159], v[204:207], v[94:97]
	v_mfma_f32_16x16x32_bf16 v[90:93], v[164:167], v[204:207], v[90:93]
	v_mfma_f32_16x16x32_bf16 v[78:81], v[156:159], v[212:215], v[78:81]
	v_mfma_f32_16x16x32_bf16 v[74:77], v[164:167], v[212:215], v[74:77]
	v_mfma_f32_16x16x32_bf16 v[126:129], v[160:163], v[192:195], v[126:129]
	v_mfma_f32_16x16x32_bf16 v[122:125], v[168:171], v[192:195], v[122:125]
	v_mfma_f32_16x16x32_bf16 v[110:113], v[160:163], v[200:203], v[110:113]
	v_mfma_f32_16x16x32_bf16 v[106:109], v[168:171], v[200:203], v[106:109]
	v_mfma_f32_16x16x32_bf16 v[94:97], v[160:163], v[208:211], v[94:97]
	v_mfma_f32_16x16x32_bf16 v[90:93], v[168:171], v[208:211], v[90:93]
	v_mfma_f32_16x16x32_bf16 v[78:81], v[160:163], v[216:219], v[78:81]
	v_mfma_f32_16x16x32_bf16 v[74:77], v[168:171], v[216:219], v[74:77]
	s_setprio 0
	s_setprio 1
	v_mfma_f32_16x16x32_bf16 v[118:121], v[172:175], v[188:191], v[118:121]
	v_mfma_f32_16x16x32_bf16 v[114:117], v[180:183], v[188:191], v[114:117]
	v_mfma_f32_16x16x32_bf16 v[102:105], v[172:175], v[196:199], v[102:105]
	v_mfma_f32_16x16x32_bf16 v[98:101], v[180:183], v[196:199], v[98:101]
	v_mfma_f32_16x16x32_bf16 v[86:89], v[172:175], v[204:207], v[86:89]
	v_mfma_f32_16x16x32_bf16 v[82:85], v[180:183], v[204:207], v[82:85]
	v_mfma_f32_16x16x32_bf16 v[70:73], v[172:175], v[212:215], v[70:73]
	v_mfma_f32_16x16x32_bf16 v[66:69], v[180:183], v[212:215], v[66:69]
	v_mfma_f32_16x16x32_bf16 v[118:121], v[176:179], v[192:195], v[118:121]
	v_mfma_f32_16x16x32_bf16 v[114:117], v[184:187], v[192:195], v[114:117]
	v_mfma_f32_16x16x32_bf16 v[102:105], v[176:179], v[200:203], v[102:105]
	v_mfma_f32_16x16x32_bf16 v[98:101], v[184:187], v[200:203], v[98:101]
	v_mfma_f32_16x16x32_bf16 v[86:89], v[176:179], v[208:211], v[86:89]
	v_mfma_f32_16x16x32_bf16 v[82:85], v[184:187], v[208:211], v[82:85]
	v_mfma_f32_16x16x32_bf16 v[70:73], v[176:179], v[216:219], v[70:73]
	v_mfma_f32_16x16x32_bf16 v[66:69], v[184:187], v[216:219], v[66:69]
	s_setprio 0
	s_barrier
	s_add_i32 s6, s63, s31
	v_lshl_add_u64 v[148:149], s[50:51], 0, v[132:133]
	s_mov_b32 m0, s6
	ds_read_b128 v[188:191], v154 offset:16384
	ds_read_b128 v[192:195], v154 offset:17408
	ds_read_b128 v[196:199], v154 offset:18432
	ds_read_b128 v[200:203], v154 offset:19456
	ds_read_b128 v[204:207], v154 offset:20480
	ds_read_b128 v[208:211], v154 offset:21504
	ds_read_b128 v[212:215], v154 offset:22528
	ds_read_b128 v[216:219], v154 offset:23552
	global_load_lds_dwordx4 v[148:149], off
	s_add_i32 m0, s6, 0x2000
	s_add_u32 s6, s50, 0x40000
	v_lshl_add_u64 v[220:221], s[50:51], 0, v[136:137]
	s_addc_u32 s7, s51, 0
	s_add_i32 s83, s64, s31
	global_load_lds_dwordx4 v[220:221], off
	v_lshl_add_u64 v[222:223], s[6:7], 0, v[132:133]
	s_mov_b32 m0, s83
	v_lshl_add_u64 v[224:225], s[52:53], 0, v[134:135]
	global_load_lds_dwordx4 v[222:223], off
	v_lshl_add_u64 v[222:223], s[6:7], 0, v[136:137]
	s_add_i32 m0, s83, 0x2000
	s_nop 0
	global_load_lds_dwordx4 v[222:223], off
	v_lshl_add_u64 v[222:223], s[52:53], 0, v[130:131]
	s_mov_b32 m0, s54
	s_nop 0
	global_load_lds_dwordx4 v[222:223], off
	s_mov_b32 m0, s55
	s_nop 0
	global_load_lds_dwordx4 v[224:225], off
	s_waitcnt vmcnt(8)
	s_waitcnt lgkmcnt(0)
	s_barrier
	s_setprio 1
	s_waitcnt lgkmcnt(0)
	v_mfma_f32_16x16x32_bf16 v[62:65], v[156:159], v[188:191], v[62:65]
	v_mfma_f32_16x16x32_bf16 v[58:61], v[164:167], v[188:191], v[58:61]
	v_mfma_f32_16x16x32_bf16 v[46:49], v[156:159], v[196:199], v[46:49]
	v_mfma_f32_16x16x32_bf16 v[42:45], v[164:167], v[196:199], v[42:45]
	v_mfma_f32_16x16x32_bf16 v[30:33], v[156:159], v[204:207], v[30:33]
	v_mfma_f32_16x16x32_bf16 v[26:29], v[164:167], v[204:207], v[26:29]
	v_mfma_f32_16x16x32_bf16 v[14:17], v[156:159], v[212:215], v[14:17]
	v_mfma_f32_16x16x32_bf16 v[10:13], v[164:167], v[212:215], v[10:13]
	v_mfma_f32_16x16x32_bf16 v[62:65], v[160:163], v[192:195], v[62:65]
	v_mfma_f32_16x16x32_bf16 v[58:61], v[168:171], v[192:195], v[58:61]
	v_mfma_f32_16x16x32_bf16 v[46:49], v[160:163], v[200:203], v[46:49]
	v_mfma_f32_16x16x32_bf16 v[42:45], v[168:171], v[200:203], v[42:45]
	v_mfma_f32_16x16x32_bf16 v[30:33], v[160:163], v[208:211], v[30:33]
	v_mfma_f32_16x16x32_bf16 v[26:29], v[168:171], v[208:211], v[26:29]
	v_mfma_f32_16x16x32_bf16 v[14:17], v[160:163], v[216:219], v[14:17]
	v_mfma_f32_16x16x32_bf16 v[10:13], v[168:171], v[216:219], v[10:13]
	s_setprio 0
	s_setprio 1
	v_mfma_f32_16x16x32_bf16 v[54:57], v[172:175], v[188:191], v[54:57]
	v_mfma_f32_16x16x32_bf16 v[50:53], v[180:183], v[188:191], v[50:53]
	v_mfma_f32_16x16x32_bf16 v[38:41], v[172:175], v[196:199], v[38:41]
	v_mfma_f32_16x16x32_bf16 v[34:37], v[180:183], v[196:199], v[34:37]
	v_mfma_f32_16x16x32_bf16 v[22:25], v[172:175], v[204:207], v[22:25]
	v_mfma_f32_16x16x32_bf16 v[18:21], v[180:183], v[204:207], v[18:21]
	v_mfma_f32_16x16x32_bf16 v[6:9], v[172:175], v[212:215], v[6:9]
	v_mfma_f32_16x16x32_bf16 v[2:5], v[180:183], v[212:215], v[2:5]
	v_mfma_f32_16x16x32_bf16 v[54:57], v[176:179], v[192:195], v[54:57]
	v_mfma_f32_16x16x32_bf16 v[50:53], v[184:187], v[192:195], v[50:53]
	v_mfma_f32_16x16x32_bf16 v[38:41], v[176:179], v[200:203], v[38:41]
	v_mfma_f32_16x16x32_bf16 v[34:37], v[184:187], v[200:203], v[34:37]
	v_mfma_f32_16x16x32_bf16 v[22:25], v[176:179], v[208:211], v[22:25]
	v_mfma_f32_16x16x32_bf16 v[18:21], v[184:187], v[208:211], v[18:21]
	v_mfma_f32_16x16x32_bf16 v[6:9], v[176:179], v[216:219], v[6:9]
	v_mfma_f32_16x16x32_bf16 v[2:5], v[184:187], v[216:219], v[2:5]
	s_setprio 0
	s_barrier
	s_add_i32 s83, 0, 0x18000
	v_add_u32_e32 v138, s83, v151
	s_add_i32 s84, 0, 0x1c000
	ds_read_b128 v[156:159], v138
	ds_read_b128 v[160:163], v138 offset:1024
	ds_read_b128 v[164:167], v138 offset:2048
	ds_read_b128 v[168:171], v138 offset:3072
	v_add_u32_e32 v138, s84, v151
	ds_read_b128 v[172:175], v138
	ds_read_b128 v[176:179], v138 offset:1024
	ds_read_b128 v[180:183], v138 offset:2048
	ds_read_b128 v[184:187], v138 offset:3072
	s_add_u32 s6, s52, 0x40000
	s_addc_u32 s7, s53, 0
	s_mov_b32 m0, s56
	v_lshl_add_u64 v[226:227], s[6:7], 0, v[130:131]
	ds_read_b128 v[188:191], v154 offset:32768
	ds_read_b128 v[192:195], v154 offset:33792
	ds_read_b128 v[196:199], v154 offset:34816
	ds_read_b128 v[200:203], v154 offset:35840
	ds_read_b128 v[204:207], v154 offset:36864
	ds_read_b128 v[208:211], v154 offset:37888
	ds_read_b128 v[212:215], v154 offset:38912
	ds_read_b128 v[216:219], v154 offset:39936
	global_load_lds_dwordx4 v[226:227], off
	v_lshl_add_u64 v[226:227], s[6:7], 0, v[134:135]
	s_mov_b32 m0, s57
	s_nop 0
	global_load_lds_dwordx4 v[226:227], off
	s_waitcnt vmcnt(8)
	s_waitcnt lgkmcnt(0)
	s_barrier
	s_setprio 1
	s_waitcnt lgkmcnt(0)
	v_mfma_f32_16x16x32_bf16 v[126:129], v[156:159], v[188:191], v[126:129]
	v_mfma_f32_16x16x32_bf16 v[122:125], v[164:167], v[188:191], v[122:125]
	v_mfma_f32_16x16x32_bf16 v[110:113], v[156:159], v[196:199], v[110:113]
	v_mfma_f32_16x16x32_bf16 v[106:109], v[164:167], v[196:199], v[106:109]
	v_mfma_f32_16x16x32_bf16 v[94:97], v[156:159], v[204:207], v[94:97]
	v_mfma_f32_16x16x32_bf16 v[90:93], v[164:167], v[204:207], v[90:93]
	v_mfma_f32_16x16x32_bf16 v[78:81], v[156:159], v[212:215], v[78:81]
	v_mfma_f32_16x16x32_bf16 v[74:77], v[164:167], v[212:215], v[74:77]
	v_mfma_f32_16x16x32_bf16 v[126:129], v[160:163], v[192:195], v[126:129]
	v_mfma_f32_16x16x32_bf16 v[122:125], v[168:171], v[192:195], v[122:125]
	v_mfma_f32_16x16x32_bf16 v[110:113], v[160:163], v[200:203], v[110:113]
	v_mfma_f32_16x16x32_bf16 v[106:109], v[168:171], v[200:203], v[106:109]
	v_mfma_f32_16x16x32_bf16 v[94:97], v[160:163], v[208:211], v[94:97]
	v_mfma_f32_16x16x32_bf16 v[90:93], v[168:171], v[208:211], v[90:93]
	v_mfma_f32_16x16x32_bf16 v[78:81], v[160:163], v[216:219], v[78:81]
	v_mfma_f32_16x16x32_bf16 v[74:77], v[168:171], v[216:219], v[74:77]
	s_setprio 0
	s_setprio 1
	v_mfma_f32_16x16x32_bf16 v[118:121], v[172:175], v[188:191], v[118:121]
	v_mfma_f32_16x16x32_bf16 v[114:117], v[180:183], v[188:191], v[114:117]
	v_mfma_f32_16x16x32_bf16 v[102:105], v[172:175], v[196:199], v[102:105]
	v_mfma_f32_16x16x32_bf16 v[98:101], v[180:183], v[196:199], v[98:101]
	v_mfma_f32_16x16x32_bf16 v[86:89], v[172:175], v[204:207], v[86:89]
	v_mfma_f32_16x16x32_bf16 v[82:85], v[180:183], v[204:207], v[82:85]
	v_mfma_f32_16x16x32_bf16 v[70:73], v[172:175], v[212:215], v[70:73]
	v_mfma_f32_16x16x32_bf16 v[66:69], v[180:183], v[212:215], v[66:69]
	v_mfma_f32_16x16x32_bf16 v[118:121], v[176:179], v[192:195], v[118:121]
	v_mfma_f32_16x16x32_bf16 v[114:117], v[184:187], v[192:195], v[114:117]
	v_mfma_f32_16x16x32_bf16 v[102:105], v[176:179], v[200:203], v[102:105]
	v_mfma_f32_16x16x32_bf16 v[98:101], v[184:187], v[200:203], v[98:101]
	v_mfma_f32_16x16x32_bf16 v[86:89], v[176:179], v[208:211], v[86:89]
	v_mfma_f32_16x16x32_bf16 v[82:85], v[184:187], v[208:211], v[82:85]
	v_mfma_f32_16x16x32_bf16 v[70:73], v[176:179], v[216:219], v[70:73]
	v_mfma_f32_16x16x32_bf16 v[66:69], v[184:187], v[216:219], v[66:69]
	s_setprio 0
	s_barrier
	s_add_i32 s6, s83, s31
	v_lshl_add_u64 v[148:149], v[148:149], 0, s[16:17]
	s_mov_b32 m0, s6
	ds_read_b128 v[188:191], v154 offset:49152
	ds_read_b128 v[192:195], v154 offset:50176
	ds_read_b128 v[196:199], v154 offset:51200
	ds_read_b128 v[200:203], v154 offset:52224
	ds_read_b128 v[204:207], v154 offset:53248
	ds_read_b128 v[208:211], v154 offset:54272
	ds_read_b128 v[212:215], v154 offset:55296
	ds_read_b128 v[216:219], v154 offset:56320
	global_load_lds_dwordx4 v[148:149], off
	s_add_i32 m0, s6, 0x2000
	s_add_u32 s6, s50, 0x40080
	v_lshl_add_u64 v[148:149], v[220:221], 0, s[16:17]
	s_addc_u32 s7, s51, 0
	s_add_i32 s50, s84, s31
	global_load_lds_dwordx4 v[148:149], off
	v_lshl_add_u64 v[148:149], s[6:7], 0, v[132:133]
	s_mov_b32 m0, s50
	s_nop 0
	global_load_lds_dwordx4 v[148:149], off
	v_lshl_add_u64 v[148:149], s[6:7], 0, v[136:137]
	s_add_i32 m0, s50, 0x2000
	s_nop 0
	global_load_lds_dwordx4 v[148:149], off
	v_lshl_add_u64 v[148:149], v[222:223], 0, s[16:17]
	s_mov_b32 m0, s60
	s_nop 0
	global_load_lds_dwordx4 v[148:149], off
	v_lshl_add_u64 v[148:149], v[224:225], 0, s[16:17]
	s_mov_b32 m0, s61
	s_nop 0
	global_load_lds_dwordx4 v[148:149], off
	s_waitcnt vmcnt(8)
	s_waitcnt lgkmcnt(0)
	s_barrier
	s_setprio 1
	s_waitcnt lgkmcnt(0)
	v_mfma_f32_16x16x32_bf16 v[62:65], v[156:159], v[188:191], v[62:65]
	v_mfma_f32_16x16x32_bf16 v[58:61], v[164:167], v[188:191], v[58:61]
	v_mfma_f32_16x16x32_bf16 v[46:49], v[156:159], v[196:199], v[46:49]
	v_mfma_f32_16x16x32_bf16 v[42:45], v[164:167], v[196:199], v[42:45]
	v_mfma_f32_16x16x32_bf16 v[30:33], v[156:159], v[204:207], v[30:33]
	v_mfma_f32_16x16x32_bf16 v[26:29], v[164:167], v[204:207], v[26:29]
	v_mfma_f32_16x16x32_bf16 v[14:17], v[156:159], v[212:215], v[14:17]
	v_mfma_f32_16x16x32_bf16 v[10:13], v[164:167], v[212:215], v[10:13]
	v_mfma_f32_16x16x32_bf16 v[62:65], v[160:163], v[192:195], v[62:65]
	v_mfma_f32_16x16x32_bf16 v[58:61], v[168:171], v[192:195], v[58:61]
	v_mfma_f32_16x16x32_bf16 v[46:49], v[160:163], v[200:203], v[46:49]
	v_mfma_f32_16x16x32_bf16 v[42:45], v[168:171], v[200:203], v[42:45]
	v_mfma_f32_16x16x32_bf16 v[30:33], v[160:163], v[208:211], v[30:33]
	v_mfma_f32_16x16x32_bf16 v[26:29], v[168:171], v[208:211], v[26:29]
	v_mfma_f32_16x16x32_bf16 v[14:17], v[160:163], v[216:219], v[14:17]
	v_mfma_f32_16x16x32_bf16 v[10:13], v[168:171], v[216:219], v[10:13]
	s_setprio 0
	s_setprio 1
	v_mfma_f32_16x16x32_bf16 v[54:57], v[172:175], v[188:191], v[54:57]
	v_mfma_f32_16x16x32_bf16 v[50:53], v[180:183], v[188:191], v[50:53]
	v_mfma_f32_16x16x32_bf16 v[38:41], v[172:175], v[196:199], v[38:41]
	v_mfma_f32_16x16x32_bf16 v[34:37], v[180:183], v[196:199], v[34:37]
	v_mfma_f32_16x16x32_bf16 v[22:25], v[172:175], v[204:207], v[22:25]
	v_mfma_f32_16x16x32_bf16 v[18:21], v[180:183], v[204:207], v[18:21]
	v_mfma_f32_16x16x32_bf16 v[6:9], v[172:175], v[212:215], v[6:9]
	v_mfma_f32_16x16x32_bf16 v[2:5], v[180:183], v[212:215], v[2:5]
	v_mfma_f32_16x16x32_bf16 v[54:57], v[176:179], v[192:195], v[54:57]
	v_mfma_f32_16x16x32_bf16 v[50:53], v[184:187], v[192:195], v[50:53]
	v_mfma_f32_16x16x32_bf16 v[38:41], v[176:179], v[200:203], v[38:41]
	v_mfma_f32_16x16x32_bf16 v[34:37], v[184:187], v[200:203], v[34:37]
	v_mfma_f32_16x16x32_bf16 v[22:25], v[176:179], v[208:211], v[22:25]
	v_mfma_f32_16x16x32_bf16 v[18:21], v[184:187], v[208:211], v[18:21]
	v_mfma_f32_16x16x32_bf16 v[6:9], v[176:179], v[216:219], v[6:9]
	v_mfma_f32_16x16x32_bf16 v[2:5], v[184:187], v[216:219], v[2:5]
	s_setprio 0
	s_cmp_gt_u32 s99, 4
	s_cbranch_scc0 .Lpk6_go
.Lpk6_back:
	s_add_i32 s82, s82, 2
	s_add_u32 s48, s48, 0x100
	s_addc_u32 s49, s49, 0
	s_add_u32 s80, s80, 0x100
	s_addc_u32 s81, s81, 0
	s_cmp_gt_u32 s82, 13
	s_barrier
	s_cbranch_scc0 .LBB0_780

.LBB0_855:
	ds_read_b128 v[118:121], v193
	ds_read_b128 v[126:129], v193 offset:1024
	ds_read_b128 v[130:133], v193 offset:2048
	ds_read_b128 v[134:137], v193 offset:3072
	ds_read_b128 v[160:163], v194
	ds_read_b128 v[164:167], v194 offset:1024
	ds_read_b128 v[168:171], v194 offset:2048
	ds_read_b128 v[172:175], v194 offset:3072
	v_lshl_add_u64 v[188:189], s[4:5], 0, v[150:151]
	s_add_i32 m0, s64, 0xc000
	ds_read_b128 v[176:179], v195
	ds_read_b128 v[180:183], v195 offset:1024
	ds_read_b128 v[184:187], v195 offset:2048
	ds_read_b128 v[198:201], v195 offset:3072
	ds_read_b128 v[202:205], v195 offset:4096
	ds_read_b128 v[206:209], v195 offset:5120
	ds_read_b128 v[210:213], v195 offset:6144
	ds_read_b128 v[214:217], v195 offset:7168
	global_load_lds_dwordx4 v[188:189], off
	v_lshl_add_u64 v[188:189], s[4:5], 0, v[152:153]
	s_add_i32 m0, s64, 0xe000
	s_nop 0
	global_load_lds_dwordx4 v[188:189], off
	s_add_u32 s8, s4, 0xfff00080
	s_addc_u32 s9, s5, -1
	s_cmp_eq_u32 s61, 60
	s_cselect_b32 s59, s7, s9
	s_cselect_b32 s58, s10, s8
	s_cselect_b32 s9, s49, s60
	s_cselect_b32 s8, s51, s57
	s_waitcnt vmcnt(8)
	s_waitcnt lgkmcnt(0)
	s_barrier
	s_setprio 1
	s_waitcnt lgkmcnt(0)
	v_mfma_f32_16x16x32_bf16 v[142:145], v[118:121], v[176:179], v[142:145]
	v_mfma_f32_16x16x32_bf16 v[138:141], v[130:133], v[176:179], v[138:141]
	v_mfma_f32_16x16x32_bf16 v[110:113], v[118:121], v[184:187], v[110:113]
	v_mfma_f32_16x16x32_bf16 v[106:109], v[130:133], v[184:187], v[106:109]
	v_mfma_f32_16x16x32_bf16 v[94:97], v[118:121], v[202:205], v[94:97]
	v_mfma_f32_16x16x32_bf16 v[90:93], v[130:133], v[202:205], v[90:93]
	v_mfma_f32_16x16x32_bf16 v[78:81], v[118:121], v[210:213], v[78:81]
	v_mfma_f32_16x16x32_bf16 v[74:77], v[130:133], v[210:213], v[74:77]
	v_mfma_f32_16x16x32_bf16 v[142:145], v[126:129], v[180:183], v[142:145]
	v_mfma_f32_16x16x32_bf16 v[138:141], v[134:137], v[180:183], v[138:141]
	v_mfma_f32_16x16x32_bf16 v[110:113], v[126:129], v[198:201], v[110:113]
	v_mfma_f32_16x16x32_bf16 v[106:109], v[134:137], v[198:201], v[106:109]
	v_mfma_f32_16x16x32_bf16 v[94:97], v[126:129], v[206:209], v[94:97]
	v_mfma_f32_16x16x32_bf16 v[90:93], v[134:137], v[206:209], v[90:93]
	v_mfma_f32_16x16x32_bf16 v[78:81], v[126:129], v[214:217], v[78:81]
	v_mfma_f32_16x16x32_bf16 v[74:77], v[134:137], v[214:217], v[74:77]
	s_setprio 0
	s_setprio 1
	v_mfma_f32_16x16x32_bf16 v[122:125], v[160:163], v[176:179], v[122:125]
	v_mfma_f32_16x16x32_bf16 v[114:117], v[168:171], v[176:179], v[114:117]
	v_mfma_f32_16x16x32_bf16 v[102:105], v[160:163], v[184:187], v[102:105]
	v_mfma_f32_16x16x32_bf16 v[98:101], v[168:171], v[184:187], v[98:101]
	v_mfma_f32_16x16x32_bf16 v[86:89], v[160:163], v[202:205], v[86:89]
	v_mfma_f32_16x16x32_bf16 v[82:85], v[168:171], v[202:205], v[82:85]
	v_mfma_f32_16x16x32_bf16 v[70:73], v[160:163], v[210:213], v[70:73]
	v_mfma_f32_16x16x32_bf16 v[66:69], v[168:171], v[210:213], v[66:69]
	v_mfma_f32_16x16x32_bf16 v[122:125], v[164:167], v[180:183], v[122:125]
	v_mfma_f32_16x16x32_bf16 v[114:117], v[172:175], v[180:183], v[114:117]
	v_mfma_f32_16x16x32_bf16 v[102:105], v[164:167], v[198:201], v[102:105]
	v_mfma_f32_16x16x32_bf16 v[98:101], v[172:175], v[198:201], v[98:101]
	v_mfma_f32_16x16x32_bf16 v[86:89], v[164:167], v[206:209], v[86:89]
	v_mfma_f32_16x16x32_bf16 v[82:85], v[172:175], v[206:209], v[82:85]
	v_mfma_f32_16x16x32_bf16 v[70:73], v[164:167], v[214:217], v[70:73]
	v_mfma_f32_16x16x32_bf16 v[66:69], v[172:175], v[214:217], v[66:69]
	s_setprio 0
	s_barrier
	s_add_i32 s62, s84, s33
	v_lshl_add_u64 v[188:189], s[8:9], 0, v[146:147]
	s_mov_b32 m0, s62
	ds_read_b128 v[176:179], v195 offset:16384
	ds_read_b128 v[180:183], v195 offset:17408
	ds_read_b128 v[184:187], v195 offset:18432
	ds_read_b128 v[198:201], v195 offset:19456
	ds_read_b128 v[202:205], v195 offset:20480
	ds_read_b128 v[206:209], v195 offset:21504
	ds_read_b128 v[210:213], v195 offset:22528
	ds_read_b128 v[214:217], v195 offset:23552
	global_load_lds_dwordx4 v[188:189], off
	s_add_i32 m0, s62, 0x2000
	s_add_u32 s62, s8, 0x100000
	v_lshl_add_u64 v[218:219], s[8:9], 0, v[148:149]
	s_addc_u32 s63, s9, 0
	s_add_i32 s92, s85, s33
	global_load_lds_dwordx4 v[218:219], off
	v_lshl_add_u64 v[220:221], s[62:63], 0, v[146:147]
	s_mov_b32 m0, s92
	v_lshl_add_u64 v[222:223], s[58:59], 0, v[148:149]
	global_load_lds_dwordx4 v[220:221], off
	v_lshl_add_u64 v[220:221], s[62:63], 0, v[148:149]
	s_add_i32 m0, s92, 0x2000
	s_nop 0
	global_load_lds_dwordx4 v[220:221], off
	v_lshl_add_u64 v[220:221], s[58:59], 0, v[146:147]
	s_mov_b32 m0, s64
	s_nop 0
	global_load_lds_dwordx4 v[220:221], off
	s_mov_b32 m0, s65
	s_nop 0
	global_load_lds_dwordx4 v[222:223], off
	s_waitcnt vmcnt(8)
	s_waitcnt lgkmcnt(0)
	s_barrier
	s_setprio 1
	s_waitcnt lgkmcnt(0)
	v_mfma_f32_16x16x32_bf16 v[58:61], v[118:121], v[176:179], v[58:61]
	v_mfma_f32_16x16x32_bf16 v[62:65], v[130:133], v[176:179], v[62:65]
	v_mfma_f32_16x16x32_bf16 v[46:49], v[118:121], v[184:187], v[46:49]
	v_mfma_f32_16x16x32_bf16 v[42:45], v[130:133], v[184:187], v[42:45]
	v_mfma_f32_16x16x32_bf16 v[30:33], v[118:121], v[202:205], v[30:33]
	v_mfma_f32_16x16x32_bf16 v[26:29], v[130:133], v[202:205], v[26:29]
	v_mfma_f32_16x16x32_bf16 v[14:17], v[118:121], v[210:213], v[14:17]
	v_mfma_f32_16x16x32_bf16 v[10:13], v[130:133], v[210:213], v[10:13]
	v_mfma_f32_16x16x32_bf16 v[58:61], v[126:129], v[180:183], v[58:61]
	v_mfma_f32_16x16x32_bf16 v[62:65], v[134:137], v[180:183], v[62:65]
	v_mfma_f32_16x16x32_bf16 v[46:49], v[126:129], v[198:201], v[46:49]
	v_mfma_f32_16x16x32_bf16 v[42:45], v[134:137], v[198:201], v[42:45]
	v_mfma_f32_16x16x32_bf16 v[30:33], v[126:129], v[206:209], v[30:33]
	v_mfma_f32_16x16x32_bf16 v[26:29], v[134:137], v[206:209], v[26:29]
	v_mfma_f32_16x16x32_bf16 v[14:17], v[126:129], v[214:217], v[14:17]
	v_mfma_f32_16x16x32_bf16 v[10:13], v[134:137], v[214:217], v[10:13]
	s_setprio 0
	s_setprio 1
	v_mfma_f32_16x16x32_bf16 v[54:57], v[160:163], v[176:179], v[54:57]
	v_mfma_f32_16x16x32_bf16 v[50:53], v[168:171], v[176:179], v[50:53]
	v_mfma_f32_16x16x32_bf16 v[38:41], v[160:163], v[184:187], v[38:41]
	v_mfma_f32_16x16x32_bf16 v[34:37], v[168:171], v[184:187], v[34:37]
	v_mfma_f32_16x16x32_bf16 v[22:25], v[160:163], v[202:205], v[22:25]
	v_mfma_f32_16x16x32_bf16 v[18:21], v[168:171], v[202:205], v[18:21]
	v_mfma_f32_16x16x32_bf16 v[6:9], v[160:163], v[210:213], v[6:9]
	v_mfma_f32_16x16x32_bf16 v[2:5], v[168:171], v[210:213], v[2:5]
	v_mfma_f32_16x16x32_bf16 v[54:57], v[164:167], v[180:183], v[54:57]
	v_mfma_f32_16x16x32_bf16 v[50:53], v[172:175], v[180:183], v[50:53]
	v_mfma_f32_16x16x32_bf16 v[38:41], v[164:167], v[198:201], v[38:41]
	v_mfma_f32_16x16x32_bf16 v[34:37], v[172:175], v[198:201], v[34:37]
	v_mfma_f32_16x16x32_bf16 v[22:25], v[164:167], v[206:209], v[22:25]
	v_mfma_f32_16x16x32_bf16 v[18:21], v[172:175], v[206:209], v[18:21]
	v_mfma_f32_16x16x32_bf16 v[6:9], v[164:167], v[214:217], v[6:9]
	v_mfma_f32_16x16x32_bf16 v[2:5], v[172:175], v[214:217], v[2:5]
	s_setprio 0
	s_barrier
	s_add_i32 s62, 0, 0x18000
	s_add_i32 s63, 0, 0x1c000
	v_add_u32_e32 v134, s62, v192
	v_add_u32_e32 v172, s63, v192
	ds_read_b128 v[118:121], v134
	ds_read_b128 v[126:129], v134 offset:1024
	ds_read_b128 v[130:133], v134 offset:2048
	ds_read_b128 v[134:137], v134 offset:3072
	ds_read_b128 v[160:163], v172
	ds_read_b128 v[164:167], v172 offset:1024
	ds_read_b128 v[168:171], v172 offset:2048
	ds_read_b128 v[172:175], v172 offset:3072
	s_add_u32 s58, s58, 0x100000
	s_addc_u32 s59, s59, 0
	s_mov_b32 m0, s66
	v_lshl_add_u64 v[224:225], s[58:59], 0, v[146:147]
	ds_read_b128 v[176:179], v195 offset:32768
	ds_read_b128 v[180:183], v195 offset:33792
	ds_read_b128 v[184:187], v195 offset:34816
	ds_read_b128 v[198:201], v195 offset:35840
	ds_read_b128 v[202:205], v195 offset:36864
	ds_read_b128 v[206:209], v195 offset:37888
	ds_read_b128 v[210:213], v195 offset:38912
	ds_read_b128 v[214:217], v195 offset:39936
	global_load_lds_dwordx4 v[224:225], off
	v_lshl_add_u64 v[224:225], s[58:59], 0, v[148:149]
	s_mov_b32 m0, s67
	s_nop 0
	global_load_lds_dwordx4 v[224:225], off
	s_waitcnt vmcnt(8)
	s_waitcnt lgkmcnt(0)
	s_barrier
	s_setprio 1
	s_waitcnt lgkmcnt(0)
	v_mfma_f32_16x16x32_bf16 v[142:145], v[118:121], v[176:179], v[142:145]
	v_mfma_f32_16x16x32_bf16 v[138:141], v[130:133], v[176:179], v[138:141]
	v_mfma_f32_16x16x32_bf16 v[110:113], v[118:121], v[184:187], v[110:113]
	v_mfma_f32_16x16x32_bf16 v[106:109], v[130:133], v[184:187], v[106:109]
	v_mfma_f32_16x16x32_bf16 v[94:97], v[118:121], v[202:205], v[94:97]
	v_mfma_f32_16x16x32_bf16 v[90:93], v[130:133], v[202:205], v[90:93]
	v_mfma_f32_16x16x32_bf16 v[78:81], v[118:121], v[210:213], v[78:81]
	v_mfma_f32_16x16x32_bf16 v[74:77], v[130:133], v[210:213], v[74:77]
	v_mfma_f32_16x16x32_bf16 v[142:145], v[126:129], v[180:183], v[142:145]
	v_mfma_f32_16x16x32_bf16 v[138:141], v[134:137], v[180:183], v[138:141]
	v_mfma_f32_16x16x32_bf16 v[110:113], v[126:129], v[198:201], v[110:113]
	v_mfma_f32_16x16x32_bf16 v[106:109], v[134:137], v[198:201], v[106:109]
	v_mfma_f32_16x16x32_bf16 v[94:97], v[126:129], v[206:209], v[94:97]
	v_mfma_f32_16x16x32_bf16 v[90:93], v[134:137], v[206:209], v[90:93]
	v_mfma_f32_16x16x32_bf16 v[78:81], v[126:129], v[214:217], v[78:81]
	v_mfma_f32_16x16x32_bf16 v[74:77], v[134:137], v[214:217], v[74:77]
	s_setprio 0
	s_setprio 1
	v_mfma_f32_16x16x32_bf16 v[122:125], v[160:163], v[176:179], v[122:125]
	v_mfma_f32_16x16x32_bf16 v[114:117], v[168:171], v[176:179], v[114:117]
	v_mfma_f32_16x16x32_bf16 v[102:105], v[160:163], v[184:187], v[102:105]
	v_mfma_f32_16x16x32_bf16 v[98:101], v[168:171], v[184:187], v[98:101]
	v_mfma_f32_16x16x32_bf16 v[86:89], v[160:163], v[202:205], v[86:89]
	v_mfma_f32_16x16x32_bf16 v[82:85], v[168:171], v[202:205], v[82:85]
	v_mfma_f32_16x16x32_bf16 v[70:73], v[160:163], v[210:213], v[70:73]
	v_mfma_f32_16x16x32_bf16 v[66:69], v[168:171], v[210:213], v[66:69]
	v_mfma_f32_16x16x32_bf16 v[122:125], v[164:167], v[180:183], v[122:125]
	v_mfma_f32_16x16x32_bf16 v[114:117], v[172:175], v[180:183], v[114:117]
	v_mfma_f32_16x16x32_bf16 v[102:105], v[164:167], v[198:201], v[102:105]
	v_mfma_f32_16x16x32_bf16 v[98:101], v[172:175], v[198:201], v[98:101]
	v_mfma_f32_16x16x32_bf16 v[86:89], v[164:167], v[206:209], v[86:89]
	v_mfma_f32_16x16x32_bf16 v[82:85], v[172:175], v[206:209], v[82:85]
	v_mfma_f32_16x16x32_bf16 v[70:73], v[164:167], v[214:217], v[70:73]
	v_mfma_f32_16x16x32_bf16 v[66:69], v[172:175], v[214:217], v[66:69]
	s_setprio 0
	s_barrier
	s_add_i32 s58, s62, s33
	v_lshl_add_u64 v[188:189], v[188:189], 0, s[18:19]
	s_mov_b32 m0, s58
	ds_read_b128 v[176:179], v195 offset:49152
	ds_read_b128 v[180:183], v195 offset:50176
	ds_read_b128 v[184:187], v195 offset:51200
	ds_read_b128 v[198:201], v195 offset:52224
	ds_read_b128 v[202:205], v195 offset:53248
	ds_read_b128 v[206:209], v195 offset:54272
	ds_read_b128 v[210:213], v195 offset:55296
	ds_read_b128 v[214:217], v195 offset:56320
	global_load_lds_dwordx4 v[188:189], off
	s_add_i32 m0, s58, 0x2000
	s_add_u32 s8, s8, 0x100080
	v_lshl_add_u64 v[188:189], v[218:219], 0, s[18:19]
	s_addc_u32 s9, s9, 0
	s_add_i32 s58, s63, s33
	global_load_lds_dwordx4 v[188:189], off
	v_lshl_add_u64 v[188:189], s[8:9], 0, v[146:147]
	s_mov_b32 m0, s58
	s_nop 0
	global_load_lds_dwordx4 v[188:189], off
	v_lshl_add_u64 v[188:189], s[8:9], 0, v[148:149]
	s_add_i32 m0, s58, 0x2000
	s_nop 0
	global_load_lds_dwordx4 v[188:189], off
	v_lshl_add_u64 v[188:189], v[220:221], 0, s[18:19]
	s_mov_b32 m0, s75
	s_nop 0
	global_load_lds_dwordx4 v[188:189], off
	v_lshl_add_u64 v[188:189], v[222:223], 0, s[18:19]
	s_mov_b32 m0, s76
	s_nop 0
	global_load_lds_dwordx4 v[188:189], off
	s_waitcnt vmcnt(8)
	s_waitcnt lgkmcnt(0)
	s_barrier
	s_setprio 1
	s_waitcnt lgkmcnt(0)
	v_mfma_f32_16x16x32_bf16 v[58:61], v[118:121], v[176:179], v[58:61]
	v_mfma_f32_16x16x32_bf16 v[62:65], v[130:133], v[176:179], v[62:65]
	v_mfma_f32_16x16x32_bf16 v[46:49], v[118:121], v[184:187], v[46:49]
	v_mfma_f32_16x16x32_bf16 v[42:45], v[130:133], v[184:187], v[42:45]
	v_mfma_f32_16x16x32_bf16 v[30:33], v[118:121], v[202:205], v[30:33]
	v_mfma_f32_16x16x32_bf16 v[26:29], v[130:133], v[202:205], v[26:29]
	v_mfma_f32_16x16x32_bf16 v[14:17], v[118:121], v[210:213], v[14:17]
	v_mfma_f32_16x16x32_bf16 v[10:13], v[130:133], v[210:213], v[10:13]
	v_mfma_f32_16x16x32_bf16 v[58:61], v[126:129], v[180:183], v[58:61]
	v_mfma_f32_16x16x32_bf16 v[62:65], v[134:137], v[180:183], v[62:65]
	v_mfma_f32_16x16x32_bf16 v[46:49], v[126:129], v[198:201], v[46:49]
	v_mfma_f32_16x16x32_bf16 v[42:45], v[134:137], v[198:201], v[42:45]
	v_mfma_f32_16x16x32_bf16 v[30:33], v[126:129], v[206:209], v[30:33]
	v_mfma_f32_16x16x32_bf16 v[26:29], v[134:137], v[206:209], v[26:29]
	v_mfma_f32_16x16x32_bf16 v[14:17], v[126:129], v[214:217], v[14:17]
	v_mfma_f32_16x16x32_bf16 v[10:13], v[134:137], v[214:217], v[10:13]
	s_setprio 0
	s_setprio 1
	v_mfma_f32_16x16x32_bf16 v[54:57], v[160:163], v[176:179], v[54:57]
	v_mfma_f32_16x16x32_bf16 v[50:53], v[168:171], v[176:179], v[50:53]
	v_mfma_f32_16x16x32_bf16 v[38:41], v[160:163], v[184:187], v[38:41]
	v_mfma_f32_16x16x32_bf16 v[34:37], v[168:171], v[184:187], v[34:37]
	v_mfma_f32_16x16x32_bf16 v[22:25], v[160:163], v[202:205], v[22:25]
	v_mfma_f32_16x16x32_bf16 v[18:21], v[168:171], v[202:205], v[18:21]
	v_mfma_f32_16x16x32_bf16 v[6:9], v[160:163], v[210:213], v[6:9]
	v_mfma_f32_16x16x32_bf16 v[2:5], v[168:171], v[210:213], v[2:5]
	v_mfma_f32_16x16x32_bf16 v[54:57], v[164:167], v[180:183], v[54:57]
	v_mfma_f32_16x16x32_bf16 v[50:53], v[172:175], v[180:183], v[50:53]
	v_mfma_f32_16x16x32_bf16 v[38:41], v[164:167], v[198:201], v[38:41]
	v_mfma_f32_16x16x32_bf16 v[34:37], v[172:175], v[198:201], v[34:37]
	v_mfma_f32_16x16x32_bf16 v[22:25], v[164:167], v[206:209], v[22:25]
	v_mfma_f32_16x16x32_bf16 v[18:21], v[172:175], v[206:209], v[18:21]
	v_mfma_f32_16x16x32_bf16 v[6:9], v[164:167], v[214:217], v[6:9]
	v_mfma_f32_16x16x32_bf16 v[2:5], v[172:175], v[214:217], v[2:5]
	s_setprio 0
	s_add_i32 s61, s61, 2
	s_add_u32 s4, s4, 0x100
	s_addc_u32 s5, s5, 0
	s_add_u32 s57, s57, 0x100
	s_addc_u32 s60, s60, 0
	s_cmp_gt_u32 s61, 61
	s_barrier
	s_cbranch_scc0 .LBB0_855
